# P11 tail-peel prefetch + epilogue head wait relaxed from vmcnt(0) to vmcnt(8) (next tile's DMA stays in flight through the epilogue)
# baseline (speedup 1.0000x reference)
; #define GAS __attribute__((address_space(1)))
; __device__ __forceinline__ void unpack8(const v4u w, float (&f)[8]) { f[0] = bflo(w.x); f[1] = bfhi(w.x); f[2] = bflo(w.y); f[3] = bfhi(w.y); f[4] = bflo(w.z); f[5] = bfhi(w.z); f[6] = bflo(w.w); f[7] = bfhi(w.w); }
; __device__ __forceinline__ v4u pack8(const float (&f)[8]) { v4u w; w.x = pk2(f[0], f[1]); w.y = pk2(f[2], f[3]); w.z = pk2(f[4], f[5]); w.w = pk2(f[6], f[7]); return w; }
;     __device__ __forceinline__ void operator()(const af4 (&acc)[2][2][4][2], const pg8::Unit& u, int wr_, int wc_, int fr_, int fq_) const {
;         const int tid = my_tid(), lane = tid & 63, wid = __builtin_amdgcn_readfirstlane(tid >> 6), wr = wid >> 2, wc = wid & 3, fr = lane & 15, fq = lane >> 4;
;         (void)wr_; (void)wc_; (void)fr_; (void)fq_;
;         const int chbase = u.pn * 128, grp = u.pn / 6;
;         const bf16* wsg = wsb + (size_t)grp * 128 * 128;
;         const int chl = chbase + 32 * wc + 8 * (fr >> 2) + (fr & 3);
;         float lg[2], lb[2];
; #pragma unroll
;         for (int n = 0; n < 2; ++n) { lg[n] = lng[chl + 4 * n]; lb[n] = lnb[chl + 4 * n]; }
;         v4u raw[2][4];
;         auto load_raw = [&](int ai) {
; #pragma unroll
;             for (int ks = 0; ks < 4; ++ks)
; #pragma unroll
;                 for (int n = 0; n < 2; ++n) raw[n][ks] = *(const GAS v4u*)(VT + (size_t)(chl + 4 * n) * MLAT + u.pm * 256 + ai * 128 + 32 * ks + 8 * fq);
;         };
;         load_raw(0);
; #pragma unroll
;         for (int ai = 0; ai < 2; ++ai) {
;             const int tok0 = u.pm * 256 + ai * 128;
;             bf16x8 av[2][4];
; #pragma unroll
;             for (int ks = 0; ks < 4; ++ks) {
;                 const int j0 = tok0 + 32 * ks + 8 * fq;
;                 f32x4 st[4];
; #pragma unroll
;                 for (int q = 0; q < 4; ++q) st[q] = *(const GAS f32x4*)(stats + (size_t)(j0 + 2 * q) * 2);
; #pragma unroll
;                 for (int n = 0; n < 2; ++n) {
;                     float vf[8];
;                     unpack8(raw[n][ks], vf);
; #pragma unroll
;                     for (int q = 0; q < 4; ++q) { f32x2 t = {vf[2 * q], vf[2 * q + 1]}; t = t * (f32x2){st[q].z, st[q].w} + (f32x2){st[q].x, st[q].y}; t = t * lg[n] + lb[n]; vf[2 * q] = t.x; vf[2 * q + 1] = t.y; }
;                     av[n][ks] = __builtin_bit_cast(bf16x8, pack8(vf));
.Lp11_st_nowr:
	s_waitcnt lgkmcnt(0)
	s_barrier
	v_mov_b32_e32 v164, v0
	s_mul_hi_i32 s23, s44, 0x2aaaaaab
	s_lshr_b32 s26, s23, 31
	v_readfirstlane_b32 s25, v164
	v_lshlrev_b32_e32 v130, 1, v164
	s_lshl_b32 s40, s44, 7
	s_add_i32 s44, s23, s26
	s_lshr_b32 s23, s25, 1
	v_and_b32_e32 v130, 24, v130
	v_and_b32_e32 v131, 3, v164
	s_ashr_i32 s45, s44, 31
	s_and_b32 s23, s23, 0x60
	v_or3_b32 v130, v131, v130, s40
	s_lshl_b64 s[26:27], s[44:45], 15
	v_or_b32_e32 v146, s23, v130
	v_or_b32_e32 v134, 4, v146
	s_add_u32 s52, s62, s26
	v_ashrrev_i32_e32 v147, 31, v146
	v_ashrrev_i32_e32 v135, 31, v134
	s_addc_u32 s53, s63, s27
	s_lshl_b32 s42, s6, 8
	v_lshrrev_b32_e32 v132, 1, v164
	v_lshlrev_b64 v[130:131], 15, v[146:147]
	s_ashr_i32 s43, s42, 31
	v_and_b32_e32 v209, 24, v132
	v_lshlrev_b64 v[134:135], 15, v[134:135]
	v_lshl_add_u64 v[130:131], s[50:51], 0, v[130:131]
	s_lshl_b64 s[26:27], s[42:43], 1
	v_lshl_add_u64 v[134:135], s[50:51], 0, v[134:135]
	v_or_b32_e32 v162, s42, v209
	v_lshl_add_u64 v[130:131], v[130:131], 0, s[26:27]
	v_lshlrev_b32_e32 v186, 1, v209
	v_lshl_add_u64 v[148:149], v[134:135], 0, s[26:27]
	v_ashrrev_i32_e32 v163, 31, v162
	v_lshl_add_u64 v[216:217], v[130:131], 0, v[186:187]
	v_lshl_add_u32 v150, v162, 3, s98
	v_lshl_add_u64 v[220:221], v[148:149], 0, v[186:187]
	v_mov_b64_e32 v[130:131], v[192:193]
	v_mov_b64_e32 v[132:133], v[194:195]
	ds_read_b128 v[134:137], v150 offset:16
	ds_read_b128 v[138:141], v150
	ds_read_b128 v[142:145], v150 offset:48
	ds_read_b128 v[166:169], v150 offset:32
	v_mov_b64_e32 v[170:171], v[222:223]
	v_mov_b64_e32 v[172:173], v[224:225]
	v_readlane_b32 s80, v254, 2
	v_readlane_b32 s81, v254, 3
	v_readlane_b32 s90, v254, 12
	v_readlane_b32 s91, v254, 13
	v_readlane_b32 s92, v254, 14
	v_readlane_b32 s93, v254, 15
	v_lshlrev_b64 v[146:147], 2, v[146:147]
	s_mov_b64 s[78:79], s[90:91]
	s_mov_b64 s[80:81], s[92:93]
	v_lshl_add_u64 v[148:149], s[78:79], 0, v[146:147]
	v_lshl_add_u64 v[146:147], s[80:81], 0, v[146:147]
	v_mov_b32_e32 v206, v183
	v_mov_b32_e32 v208, v179
	v_mov_b32_e32 v202, v181
	v_mov_b32_e32 v204, v185
	v_mov_b64_e32 v[174:175], v[226:227]
	v_mov_b64_e32 v[176:177], v[228:229]
	v_mov_b64_e32 v[150:151], v[234:235]
	v_mov_b64_e32 v[152:153], v[236:237]
	v_mov_b64_e32 v[158:159], v[238:239]
	v_mov_b64_e32 v[160:161], v[240:241]
	v_mov_b64_e32 v[196:197], v[242:243]
	v_mov_b64_e32 v[198:199], v[244:245]
	s_nop 0
	v_mov_b64_e32 v[146:147], v[246:247]
	v_mov_b64_e32 v[148:149], v[248:249]
	v_mov_b64_e32 v[154:155], v[250:251]
	v_mov_b64_e32 v[156:157], v[252:253]
	s_ashr_i32 s6, s25, 2
	s_andn2_b32 s6, s6, 63
	v_pk_mul_f32 v[226:227], v[126:127], s[20:21] op_sel_hi:[1,0]
	v_pk_mul_f32 v[234:235], v[122:123], v[126:127]
	v_pk_mul_f32 v[126:127], v[128:129], s[20:21] op_sel_hi:[1,0]
	v_pk_mul_f32 v[236:237], v[124:125], v[128:129]
	v_pk_mul_f32 v[128:129], v[120:121], v[120:121]
	v_pk_mul_f32 v[228:229], v[118:119], v[118:119]
	v_pk_mul_f32 v[230:231], v[114:115], s[20:21] op_sel_hi:[1,0]
	v_pk_mul_f32 v[238:239], v[118:119], v[114:115]
	v_pk_mul_f32 v[114:115], v[116:117], s[20:21] op_sel_hi:[1,0]
	v_pk_mul_f32 v[240:241], v[120:121], v[116:117]
	v_exp_f32_e32 v126, v126
	v_exp_f32_e32 v127, v127
	v_exp_f32_e32 v114, v114
	v_exp_f32_e32 v115, v115
	s_ashr_i32 s41, s40, 31
	v_pk_add_f32 v[126:127], v[126:127], 1.0 op_sel_hi:[1,0]
	s_lshl_b64 s[40:41], s[40:41], 1
	v_pk_add_f32 v[114:115], v[114:115], 1.0 op_sel_hi:[1,0]
	v_pk_mul_f32 v[252:253], v[102:103], v[98:99]
	v_pk_mul_f32 v[192:193], v[104:105], v[100:101]
	s_andn2_b64 vcc, exec, s[4:5]
	v_readlane_b32 s82, v254, 4
	v_readlane_b32 s83, v254, 5
	v_readlane_b32 s84, v254, 6
	v_readlane_b32 s85, v254, 7
	v_readlane_b32 s86, v254, 8
	v_readlane_b32 s87, v254, 9
	v_readlane_b32 s88, v254, 10
	v_readlane_b32 s89, v254, 11
	v_readlane_b32 s94, v254, 16
	v_readlane_b32 s95, v254, 17
	s_waitcnt vmcnt(8)
	s_waitcnt lgkmcnt(0)
	v_lshlrev_b32_e32 v200, 16, v130
	v_and_b32_e32 v201, 0xffff0000, v130
	v_lshlrev_b32_e32 v212, 16, v170
	v_and_b32_e32 v213, 0xffff0000, v170
	v_lshlrev_b32_e32 v130, 16, v131
	v_and_b32_e32 v131, 0xffff0000, v131
	v_lshlrev_b32_e32 v210, 16, v132
	v_and_b32_e32 v211, 0xffff0000, v132
	v_lshlrev_b32_e32 v132, 16, v133
	v_and_b32_e32 v133, 0xffff0000, v133
	v_pk_fma_f32 v[200:201], v[140:141], v[200:201], v[138:139]
	v_lshlrev_b32_e32 v170, 16, v171
	v_and_b32_e32 v171, 0xffff0000, v171
	v_pk_fma_f32 v[138:139], v[140:141], v[212:213], v[138:139]
	v_pk_fma_f32 v[130:131], v[136:137], v[130:131], v[134:135]
	v_pk_fma_f32 v[210:211], v[168:169], v[210:211], v[166:167]
	v_pk_fma_f32 v[132:133], v[144:145], v[132:133], v[142:143]
	v_lshlrev_b32_e32 v214, 16, v172
	v_and_b32_e32 v215, 0xffff0000, v172
	v_lshlrev_b32_e32 v172, 16, v173
	v_and_b32_e32 v173, 0xffff0000, v173
	v_pk_fma_f32 v[134:135], v[136:137], v[170:171], v[134:135]
	v_pk_fma_f32 v[138:139], v[202:203], v[138:139], v[204:205] op_sel_hi:[0,1,0]
	v_pk_fma_f32 v[200:201], v[208:209], v[200:201], v[206:207] op_sel_hi:[0,1,0]
	v_pk_fma_f32 v[218:219], v[208:209], v[130:131], v[206:207] op_sel_hi:[0,1,0]
	v_pk_fma_f32 v[210:211], v[208:209], v[210:211], v[206:207] op_sel_hi:[0,1,0]
	v_pk_fma_f32 v[222:223], v[208:209], v[132:133], v[206:207] op_sel_hi:[0,1,0]
	v_pk_fma_f32 v[140:141], v[144:145], v[172:173], v[142:143]
	v_cvt_pk_bf16_f32 v130, v200, v201
	v_cvt_pk_bf16_f32 v131, v218, v219
	v_cvt_pk_bf16_f32 v132, v210, v211
	v_cvt_pk_bf16_f32 v133, v222, v223
	v_pk_fma_f32 v[142:143], v[202:203], v[134:135], v[204:205] op_sel_hi:[0,1,0]
	v_cvt_pk_bf16_f32 v134, v138, v139
	v_or_b32_e32 v138, 32, v162
	v_pk_fma_f32 v[136:137], v[168:169], v[214:215], v[166:167]
	v_ashrrev_i32_e32 v139, 31, v138
	v_pk_fma_f32 v[136:137], v[202:203], v[136:137], v[204:205] op_sel_hi:[0,1,0]
	v_pk_fma_f32 v[140:141], v[202:203], v[140:141], v[204:205] op_sel_hi:[0,1,0]
	v_lshl_add_u32 v170, v138, 3, s98
	v_cvt_pk_bf16_f32 v135, v142, v143
	v_cvt_pk_bf16_f32 v136, v136, v137
	v_cvt_pk_bf16_f32 v137, v140, v141
	ds_read_b128 v[138:141], v170
	ds_read_b128 v[142:145], v170 offset:16
	ds_read_b128 v[166:169], v170 offset:32
	s_nop 0
	ds_read_b128 v[170:173], v170 offset:48
	v_or_b32_e32 v200, 64, v162
	v_lshlrev_b32_e32 v210, 16, v174
	v_and_b32_e32 v211, 0xffff0000, v174
	v_lshlrev_b32_e32 v174, 16, v175
	v_and_b32_e32 v175, 0xffff0000, v175
	v_lshlrev_b32_e32 v212, 16, v176
	v_and_b32_e32 v213, 0xffff0000, v176
	v_lshlrev_b32_e32 v176, 16, v177
	v_and_b32_e32 v177, 0xffff0000, v177
	v_lshlrev_b32_e32 v214, 16, v196
	v_and_b32_e32 v215, 0xffff0000, v196
	v_lshlrev_b32_e32 v196, 16, v197
	v_and_b32_e32 v197, 0xffff0000, v197
	v_lshlrev_b32_e32 v218, 16, v198
	v_and_b32_e32 v219, 0xffff0000, v198
	v_lshlrev_b32_e32 v198, 16, v199
	v_and_b32_e32 v199, 0xffff0000, v199
	v_ashrrev_i32_e32 v201, 31, v200
	v_lshl_add_u32 v200, v200, 3, s98
	v_or_b32_e32 v162, 0x60, v162
	v_ashrrev_i32_e32 v163, 31, v162
	v_lshl_add_u32 v162, v162, 3, s98
	v_and_b32_e32 v165, 0xffff0000, v160
	s_waitcnt lgkmcnt(3)
; #define GAS __attribute__((address_space(1)))
; __device__ __forceinline__ void unpack8(const v4u w, float (&f)[8]) { f[0] = bflo(w.x); f[1] = bfhi(w.x); f[2] = bflo(w.y); f[3] = bfhi(w.y); f[4] = bflo(w.z); f[5] = bfhi(w.z); f[6] = bflo(w.w); f[7] = bfhi(w.w); }
; __device__ __forceinline__ v4u pack8(const float (&f)[8]) { v4u w; w.x = pk2(f[0], f[1]); w.y = pk2(f[2], f[3]); w.z = pk2(f[4], f[5]); w.w = pk2(f[6], f[7]); return w; }
;     __device__ __forceinline__ void operator()(const af4 (&acc)[2][2][4][2], const pg8::Unit& u, int wr_, int wc_, int fr_, int fq_) const {
;     ...
;             for (int ks = 0; ks < 4; ++ks) {
;                 const int j0 = tok0 + 32 * ks + 8 * fq;
;                 f32x4 st[4];
; #pragma unroll
;                 for (int q = 0; q < 4; ++q) st[q] = *(const GAS f32x4*)(stats + (size_t)(j0 + 2 * q) * 2);
; #pragma unroll
;                 for (int n = 0; n < 2; ++n) {
;                     float vf[8];
;                     unpack8(raw[n][ks], vf);
; #pragma unroll
;                     for (int q = 0; q < 4; ++q) { f32x2 t = {vf[2 * q], vf[2 * q + 1]}; t = t * (f32x2){st[q].z, st[q].w} + (f32x2){st[q].x, st[q].y}; t = t * lg[n] + lb[n]; vf[2 * q] = t.x; vf[2 * q + 1] = t.y; }
;                     av[n][ks] = __builtin_bit_cast(bf16x8, pack8(vf));
;                 }
;             }
; #pragma unroll
;             for (int m = 0; m < 4; ++m) {
;                 if (ai == 0 && m == 0) load_raw(1);
;                 const int it = wr * 64 + m * 16 + fr;
;                 bf16x8 wf[4];
; #pragma unroll
;                 for (int ks = 0; ks < 4; ++ks) wf[ks] = *(const GAS bf16x8*)(wsg + (size_t)it * 128 + 32 * ks + 8 * fq);
;                 const float bsi = bs[grp * 128 + it];
	v_pk_fma_f32 v[210:211], v[140:141], v[210:211], v[138:139]
	s_waitcnt lgkmcnt(2)
	v_pk_fma_f32 v[174:175], v[144:145], v[174:175], v[142:143]
	s_waitcnt lgkmcnt(1)
	v_pk_fma_f32 v[212:213], v[168:169], v[212:213], v[166:167]
	s_waitcnt lgkmcnt(0)
	v_pk_fma_f32 v[176:177], v[172:173], v[176:177], v[170:171]
	v_pk_fma_f32 v[138:139], v[140:141], v[214:215], v[138:139]
	v_pk_fma_f32 v[140:141], v[144:145], v[196:197], v[142:143]
	v_pk_fma_f32 v[142:143], v[168:169], v[218:219], v[166:167]
	v_pk_fma_f32 v[144:145], v[172:173], v[198:199], v[170:171]
	v_pk_fma_f32 v[166:167], v[208:209], v[210:211], v[206:207] op_sel_hi:[0,1,0]
	v_pk_fma_f32 v[168:169], v[208:209], v[174:175], v[206:207] op_sel_hi:[0,1,0]
	v_pk_fma_f32 v[170:171], v[208:209], v[212:213], v[206:207] op_sel_hi:[0,1,0]
	v_pk_fma_f32 v[172:173], v[208:209], v[176:177], v[206:207] op_sel_hi:[0,1,0]
	v_pk_fma_f32 v[138:139], v[202:203], v[138:139], v[204:205] op_sel_hi:[0,1,0]
	v_pk_fma_f32 v[140:141], v[202:203], v[140:141], v[204:205] op_sel_hi:[0,1,0]
	v_pk_fma_f32 v[174:175], v[202:203], v[142:143], v[204:205] op_sel_hi:[0,1,0]
	v_pk_fma_f32 v[176:177], v[202:203], v[144:145], v[204:205] op_sel_hi:[0,1,0]
	v_cvt_pk_bf16_f32 v142, v166, v167
	v_cvt_pk_bf16_f32 v143, v168, v169
	v_cvt_pk_bf16_f32 v144, v170, v171
	v_cvt_pk_bf16_f32 v145, v172, v173
	v_cvt_pk_bf16_f32 v138, v138, v139
	v_cvt_pk_bf16_f32 v139, v140, v141
	v_cvt_pk_bf16_f32 v140, v174, v175
	v_cvt_pk_bf16_f32 v141, v176, v177
	ds_read_b128 v[166:169], v200
	ds_read_b128 v[170:173], v200 offset:16
	ds_read_b128 v[174:177], v200 offset:32
	ds_read_b128 v[196:199], v200 offset:48
	v_lshlrev_b32_e32 v200, 16, v150
	v_and_b32_e32 v201, 0xffff0000, v150
	v_lshlrev_b32_e32 v150, 16, v151
	v_and_b32_e32 v151, 0xffff0000, v151
	v_lshlrev_b32_e32 v210, 16, v152
	v_and_b32_e32 v211, 0xffff0000, v152
	v_lshlrev_b32_e32 v152, 16, v153
	v_and_b32_e32 v153, 0xffff0000, v153
	v_lshlrev_b32_e32 v212, 16, v146
	v_and_b32_e32 v213, 0xffff0000, v146
	v_lshlrev_b32_e32 v146, 16, v147
	v_and_b32_e32 v147, 0xffff0000, v147
	v_lshlrev_b32_e32 v214, 16, v148
	v_and_b32_e32 v215, 0xffff0000, v148
	v_lshlrev_b32_e32 v148, 16, v149
	v_and_b32_e32 v149, 0xffff0000, v149
	v_lshl_add_u64 v[218:219], s[52:53], 0, v[186:187]
	s_waitcnt lgkmcnt(3)
	v_pk_fma_f32 v[200:201], v[168:169], v[200:201], v[166:167]
	s_waitcnt lgkmcnt(2)
	v_pk_fma_f32 v[150:151], v[172:173], v[150:151], v[170:171]
	s_waitcnt lgkmcnt(1)
	v_pk_fma_f32 v[210:211], v[176:177], v[210:211], v[174:175]
	s_waitcnt lgkmcnt(0)
	v_pk_fma_f32 v[152:153], v[198:199], v[152:153], v[196:197]
	v_pk_fma_f32 v[166:167], v[168:169], v[212:213], v[166:167]
	v_pk_fma_f32 v[146:147], v[172:173], v[146:147], v[170:171]
	v_pk_fma_f32 v[168:169], v[176:177], v[214:215], v[174:175]
	v_pk_fma_f32 v[148:149], v[198:199], v[148:149], v[196:197]
	v_pk_fma_f32 v[170:171], v[208:209], v[200:201], v[206:207] op_sel_hi:[0,1,0]
	v_pk_fma_f32 v[172:173], v[208:209], v[150:151], v[206:207] op_sel_hi:[0,1,0]
	v_pk_fma_f32 v[174:175], v[208:209], v[210:211], v[206:207] op_sel_hi:[0,1,0]
	v_pk_fma_f32 v[176:177], v[208:209], v[152:153], v[206:207] op_sel_hi:[0,1,0]
	v_pk_fma_f32 v[166:167], v[202:203], v[166:167], v[204:205] op_sel_hi:[0,1,0]
	v_pk_fma_f32 v[196:197], v[202:203], v[146:147], v[204:205] op_sel_hi:[0,1,0]
	v_pk_fma_f32 v[168:169], v[202:203], v[168:169], v[204:205] op_sel_hi:[0,1,0]
	v_pk_fma_f32 v[198:199], v[202:203], v[148:149], v[204:205] op_sel_hi:[0,1,0]
	v_cvt_pk_bf16_f32 v150, v170, v171
	v_cvt_pk_bf16_f32 v151, v172, v173
	v_cvt_pk_bf16_f32 v152, v174, v175
	v_cvt_pk_bf16_f32 v153, v176, v177
	v_cvt_pk_bf16_f32 v146, v166, v167
	v_cvt_pk_bf16_f32 v147, v196, v197
	v_cvt_pk_bf16_f32 v148, v168, v169
	v_cvt_pk_bf16_f32 v149, v198, v199
	ds_read_b128 v[166:169], v162
	ds_read_b128 v[170:173], v162 offset:16
	ds_read_b128 v[174:177], v162 offset:32
	ds_read_b128 v[196:199], v162 offset:48
	v_and_or_b32 v210, v164, 15, s6
	v_lshl_add_u32 v162, s44, 7, v210
	v_ashrrev_i32_e32 v163, 31, v162
	v_lshl_add_u64 v[200:201], v[162:163], 2, s[76:77]
	v_lshlrev_b32_e32 v162, 16, v158
	v_and_b32_e32 v163, 0xffff0000, v158
	v_lshlrev_b32_e32 v164, 16, v160
	v_lshlrev_b32_e32 v212, 16, v154
	v_and_b32_e32 v213, 0xffff0000, v154
	v_lshlrev_b32_e32 v154, 16, v155
	v_and_b32_e32 v155, 0xffff0000, v155
	v_lshlrev_b32_e32 v158, 16, v159
	v_and_b32_e32 v159, 0xffff0000, v159
	v_lshlrev_b32_e32 v160, 16, v161
	v_and_b32_e32 v161, 0xffff0000, v161
	v_lshlrev_b32_e32 v214, 16, v156
	v_and_b32_e32 v215, 0xffff0000, v156
	v_lshlrev_b32_e32 v156, 16, v157
	v_and_b32_e32 v157, 0xffff0000, v157
	v_ashrrev_i32_e32 v211, 31, v210
	s_lshl_b32 s6, s23, 1
	s_or_b32 s23, s42, 0x80
	s_waitcnt lgkmcnt(3)
	v_pk_fma_f32 v[162:163], v[168:169], v[162:163], v[166:167]
	s_waitcnt lgkmcnt(2)
	v_pk_fma_f32 v[154:155], v[172:173], v[154:155], v[170:171]
	s_waitcnt lgkmcnt(1)
	v_pk_fma_f32 v[164:165], v[176:177], v[164:165], v[174:175]
	v_pk_fma_f32 v[158:159], v[172:173], v[158:159], v[170:171]
	s_waitcnt lgkmcnt(0)
; #define GAS __attribute__((address_space(1)))
; __device__ __forceinline__ v4u pack8(const float (&f)[8]) { v4u w; w.x = pk2(f[0], f[1]); w.y = pk2(f[2], f[3]); w.z = pk2(f[4], f[5]); w.w = pk2(f[6], f[7]); return w; }
; __device__ __forceinline__ float fexp2(float x) { return __builtin_amdgcn_exp2f(x); }
; __device__ __forceinline__ float frcp(float x) { return __builtin_amdgcn_rcpf(x); }
;     __device__ __forceinline__ void operator()(const af4 (&acc)[2][2][4][2], const pg8::Unit& u, int wr_, int wc_, int fr_, int fq_) const {
;     ...
;             for (int m = 0; m < 4; ++m) {
;                 if (ai == 0 && m == 0) load_raw(1);
;                 const int it = wr * 64 + m * 16 + fr;
;                 bf16x8 wf[4];
; #pragma unroll
;                 for (int ks = 0; ks < 4; ++ks) wf[ks] = *(const GAS bf16x8*)(wsg + (size_t)it * 128 + 32 * ks + 8 * fq);
;                 const float bsi = bs[grp * 128 + it];
;                 af4 vm[2] = {(af4){bsi, bsi, bsi, bsi}, (af4){bsi, bsi, bsi, bsi}};
; #pragma unroll
;                 for (int ks = 0; ks < 4; ++ks) {
; #pragma unroll
;                     for (int n = 0; n < 2; ++n) vm[n] = __builtin_amdgcn_mfma_f32_16x16x32_bf16(av[n][ks], wf[ks], vm[n], 0, 0, 0);
;                 }
;                 float o[8];
; #pragma unroll
;                 for (int n = 0; n < 2; ++n)
; #pragma unroll
;                     for (int e = 0; e < 4; e += 2) {
;                         const f32x2 uu = {acc[ai][0][m][n][e], acc[ai][0][m][n][e + 1]}, gg = {acc[ai][1][m][n][e], acc[ai][1][m][n][e + 1]}, vv = {vm[n][e], vm[n][e + 1]};
;                         const f32x2 ar = uu * (uu * uu * (-2.302208198f * 0.044715f) + (-2.302208198f));
;                         const f32x2 gs = gg * (-1.4426950408889634f);
;                         const f32x2 ea = {fexp2(ar.x), fexp2(ar.y)}, eb = {fexp2(gs.x), fexp2(gs.y)};
;                         const f32x2 q = eb + 1.0f, den = ea * q + q;
;                         const f32x2 r = {frcp(den.x), frcp(den.y)};
;                         const f32x2 w = (uu * gg) * vv * r;
;                         o[4 * n + e] = w.x; o[4 * n + e + 1] = w.y; }
;                 *(GAS v4u*)(Y + (size_t)(tok0 + it) * CW + chbase + 32 * wc + 8 * fq) = pack8(o);
	v_pk_fma_f32 v[160:161], v[198:199], v[160:161], v[196:197]
	v_pk_fma_f32 v[166:167], v[168:169], v[212:213], v[166:167]
	v_pk_fma_f32 v[168:169], v[176:177], v[214:215], v[174:175]
	v_pk_fma_f32 v[156:157], v[198:199], v[156:157], v[196:197]
	v_pk_fma_f32 v[162:163], v[208:209], v[162:163], v[206:207] op_sel_hi:[0,1,0]
	v_pk_fma_f32 v[164:165], v[208:209], v[164:165], v[206:207] op_sel_hi:[0,1,0]
	v_pk_fma_f32 v[154:155], v[202:203], v[154:155], v[204:205] op_sel_hi:[0,1,0]
	v_pk_fma_f32 v[158:159], v[208:209], v[158:159], v[206:207] op_sel_hi:[0,1,0]
	v_pk_fma_f32 v[160:161], v[208:209], v[160:161], v[206:207] op_sel_hi:[0,1,0]
	v_pk_fma_f32 v[170:171], v[202:203], v[166:167], v[204:205] op_sel_hi:[0,1,0]
	v_pk_fma_f32 v[172:173], v[202:203], v[168:169], v[204:205] op_sel_hi:[0,1,0]
	v_pk_fma_f32 v[156:157], v[202:203], v[156:157], v[204:205] op_sel_hi:[0,1,0]
	v_cvt_pk_bf16_f32 v166, v162, v163
	v_cvt_pk_bf16_f32 v167, v158, v159
	v_cvt_pk_bf16_f32 v168, v164, v165
	v_cvt_pk_bf16_f32 v169, v160, v161
	v_cvt_pk_bf16_f32 v162, v170, v171
	v_cvt_pk_bf16_f32 v163, v154, v155
	v_cvt_pk_bf16_f32 v164, v172, v173
	v_cvt_pk_bf16_f32 v165, v156, v157
	global_load_dword v154, v[200:201], off
	v_lshlrev_b64 v[156:157], 8, v[210:211]
	v_lshl_add_u64 v[214:215], v[218:219], 0, v[156:157]
	global_load_dwordx4 v[158:161], v[214:215], off
	global_load_dwordx4 v[170:173], v[214:215], off offset:64
	global_load_dwordx4 v[174:177], v[214:215], off offset:128
	global_load_dwordx4 v[222:225], v[214:215], off offset:192
	v_pk_mul_f32 v[156:157], v[124:125], v[124:125]
	v_pk_mul_f32 v[212:213], v[122:123], v[122:123]
	v_mov_b64_e32 v[196:197], s[18:19]
	v_pk_fma_f32 v[116:117], v[212:213], s[16:17], v[196:197] op_sel_hi:[1,0,0] neg_lo:[1,0,0] neg_hi:[1,0,0]
	v_exp_f32_e32 v212, v226
	v_exp_f32_e32 v213, v227
	v_pk_fma_f32 v[156:157], v[156:157], s[16:17], v[196:197] op_sel_hi:[1,0,0] neg_lo:[1,0,0] neg_hi:[1,0,0]
	v_pk_fma_f32 v[226:227], v[228:229], s[16:17], v[196:197] op_sel_hi:[1,0,0] neg_lo:[1,0,0] neg_hi:[1,0,0]
	v_pk_fma_f32 v[128:129], v[128:129], s[16:17], v[196:197] op_sel_hi:[1,0,0] neg_lo:[1,0,0] neg_hi:[1,0,0]
	v_exp_f32_e32 v228, v230
	v_exp_f32_e32 v229, v231
	v_pk_mul_f32 v[116:117], v[122:123], v[116:117]
	v_pk_mul_f32 v[122:123], v[124:125], v[156:157]
	v_pk_mul_f32 v[118:119], v[118:119], v[226:227]
	v_pk_mul_f32 v[120:121], v[120:121], v[128:129]
	v_exp_f32_e32 v116, v116
	v_exp_f32_e32 v117, v117
	v_exp_f32_e32 v122, v122
	v_exp_f32_e32 v123, v123
	v_exp_f32_e32 v118, v118
	v_exp_f32_e32 v119, v119
	v_exp_f32_e32 v120, v120
	v_exp_f32_e32 v121, v121
	v_pk_add_f32 v[124:125], v[212:213], 1.0 op_sel_hi:[1,0]
	v_pk_add_f32 v[128:129], v[228:229], 1.0 op_sel_hi:[1,0]
	v_pk_fma_f32 v[124:125], v[116:117], v[124:125], v[124:125]
	v_pk_fma_f32 v[122:123], v[122:123], v[126:127], v[126:127]
	v_pk_fma_f32 v[126:127], v[118:119], v[128:129], v[128:129]
	v_pk_fma_f32 v[128:129], v[120:121], v[114:115], v[114:115]
	v_mov_b64_e32 v[198:199], s[56:57]
	v_rcp_f32_e32 v244, v122
	v_add_u32_e32 v122, s42, v210
	v_rcp_f32_e32 v245, v123
	v_mad_i64_i32 v[122:123], s[26:27], v122, s61, v[198:199]
	v_lshl_add_u64 v[122:123], v[122:123], 0, s[40:41]
	v_lshl_add_u64 v[122:123], v[122:123], 0, s[6:7]
	v_rcp_f32_e32 v242, v124
	v_rcp_f32_e32 v243, v125
	v_rcp_f32_e32 v246, v126
	v_rcp_f32_e32 v247, v127
	v_rcp_f32_e32 v248, v128
	v_rcp_f32_e32 v249, v129
	v_lshl_add_u64 v[250:251], v[122:123], 0, v[186:187]
	v_or_b32_e32 v212, 16, v210
	v_ashrrev_i32_e32 v213, 31, v212
	v_add_u32_e32 v211, s42, v212
	s_waitcnt vmcnt(4)
	v_mov_b32_e32 v155, v154
	v_mov_b32_e32 v156, v154
	v_mov_b32_e32 v157, v154
	s_waitcnt vmcnt(3)
	s_nop 0
	v_mfma_f32_16x16x32_bf16 v[114:117], v[130:133], v[158:161], v[154:157]
	v_mfma_f32_16x16x32_bf16 v[118:121], v[134:137], v[158:161], v[154:157]
	s_waitcnt vmcnt(2)
	v_mfma_f32_16x16x32_bf16 v[114:117], v[142:145], v[170:173], v[114:117]
	v_mfma_f32_16x16x32_bf16 v[118:121], v[138:141], v[170:173], v[118:121]
	s_waitcnt vmcnt(1)
	v_mfma_f32_16x16x32_bf16 v[114:117], v[150:153], v[174:177], v[114:117]
	v_mfma_f32_16x16x32_bf16 v[226:229], v[146:149], v[174:177], v[118:121]
	global_load_dwordx4 v[174:177], v[216:217], off offset:256
	global_load_dwordx4 v[158:161], v[216:217], off offset:320
	global_load_dwordx4 v[170:173], v[220:221], off offset:256
	global_load_dwordx4 v[154:157], v[220:221], off offset:320
	s_waitcnt vmcnt(4)
; #define GAS __attribute__((address_space(1)))
; __device__ __forceinline__ v4u pack8(const float (&f)[8]) { v4u w; w.x = pk2(f[0], f[1]); w.y = pk2(f[2], f[3]); w.z = pk2(f[4], f[5]); w.w = pk2(f[6], f[7]); return w; }
; __device__ __forceinline__ float fexp2(float x) { return __builtin_amdgcn_exp2f(x); }
; __device__ __forceinline__ float frcp(float x) { return __builtin_amdgcn_rcpf(x); }
;     __device__ __forceinline__ void operator()(const af4 (&acc)[2][2][4][2], const pg8::Unit& u, int wr_, int wc_, int fr_, int fq_) const {
;     ...
;             for (int m = 0; m < 4; ++m) {
;                 if (ai == 0 && m == 0) load_raw(1);
;                 const int it = wr * 64 + m * 16 + fr;
;                 bf16x8 wf[4];
; #pragma unroll
;                 for (int ks = 0; ks < 4; ++ks) wf[ks] = *(const GAS bf16x8*)(wsg + (size_t)it * 128 + 32 * ks + 8 * fq);
;                 const float bsi = bs[grp * 128 + it];
;                 af4 vm[2] = {(af4){bsi, bsi, bsi, bsi}, (af4){bsi, bsi, bsi, bsi}};
; #pragma unroll
;                 for (int ks = 0; ks < 4; ++ks) {
; #pragma unroll
;                     for (int n = 0; n < 2; ++n) vm[n] = __builtin_amdgcn_mfma_f32_16x16x32_bf16(av[n][ks], wf[ks], vm[n], 0, 0, 0);
;                 }
;                 float o[8];
; #pragma unroll
;                 for (int n = 0; n < 2; ++n)
; #pragma unroll
;                     for (int e = 0; e < 4; e += 2) {
;                         const f32x2 uu = {acc[ai][0][m][n][e], acc[ai][0][m][n][e + 1]}, gg = {acc[ai][1][m][n][e], acc[ai][1][m][n][e + 1]}, vv = {vm[n][e], vm[n][e + 1]};
;                         const f32x2 ar = uu * (uu * uu * (-2.302208198f * 0.044715f) + (-2.302208198f));
;                         const f32x2 gs = gg * (-1.4426950408889634f);
;                         const f32x2 ea = {fexp2(ar.x), fexp2(ar.y)}, eb = {fexp2(gs.x), fexp2(gs.y)};
;                         const f32x2 q = eb + 1.0f, den = ea * q + q;
;                         const f32x2 r = {frcp(den.x), frcp(den.y)};
;                         const f32x2 w = (uu * gg) * vv * r;
;                         o[4 * n + e] = w.x; o[4 * n + e + 1] = w.y; }
;                 *(GAS v4u*)(Y + (size_t)(tok0 + it) * CW + chbase + 32 * wc + 8 * fq) = pack8(o);
	v_mfma_f32_16x16x32_bf16 v[230:233], v[166:169], v[222:225], v[114:117]
	global_load_dwordx4 v[126:129], v[216:217], off offset:384
	global_load_dwordx4 v[118:121], v[216:217], off offset:448
	global_load_dwordx4 v[122:125], v[220:221], off offset:384
	global_load_dwordx4 v[114:117], v[220:221], off offset:448
	v_mfma_f32_16x16x32_bf16 v[220:223], v[162:165], v[222:225], v[226:229]
	s_nop 2
	v_mul_f32_e64 v216, v234, v230
	v_mul_f32_e64 v217, v235, v231
	v_pk_mul_f32 v[224:225], v[236:237], v[232:233]
	v_pk_mul_f32 v[216:217], v[242:243], v[216:217]
	v_pk_mul_f32 v[224:225], v[244:245], v[224:225]
	v_pk_mul_f32 v[242:243], v[110:111], s[20:21] op_sel_hi:[1,0]
	v_pk_mul_f32 v[220:221], v[238:239], v[220:221]
	v_pk_mul_f32 v[222:223], v[240:241], v[222:223]
	v_pk_mul_f32 v[226:227], v[246:247], v[220:221]
	v_pk_mul_f32 v[228:229], v[248:249], v[222:223]
	v_cvt_pk_bf16_f32 v220, v216, v217
	v_cvt_pk_bf16_f32 v221, v224, v225
	v_cvt_pk_bf16_f32 v222, v226, v227
	v_lshlrev_b64 v[216:217], 8, v[212:213]
	v_cvt_pk_bf16_f32 v223, v228, v229
	global_store_dwordx4 v[250:251], v[220:223], off
	global_load_dword v220, v[200:201], off offset:64
	v_lshl_add_u64 v[216:217], v[218:219], 0, v[216:217]
	global_load_dwordx4 v[224:227], v[216:217], off
	global_load_dwordx4 v[228:231], v[216:217], off offset:64
	global_load_dwordx4 v[232:235], v[216:217], off offset:128
	global_load_dwordx4 v[236:239], v[216:217], off offset:192
	v_pk_mul_f32 v[222:223], v[108:109], v[108:109]
	v_pk_mul_f32 v[240:241], v[106:107], v[106:107]
	v_pk_mul_f32 v[244:245], v[112:113], s[20:21] op_sel_hi:[1,0]
	v_pk_mul_f32 v[248:249], v[102:103], v[102:103]
	v_pk_mul_f32 v[250:251], v[98:99], s[20:21] op_sel_hi:[1,0]
	v_pk_mul_f32 v[98:99], v[100:101], s[20:21] op_sel_hi:[1,0]
	v_pk_fma_f32 v[100:101], v[240:241], s[16:17], v[196:197] op_sel_hi:[1,0,0] neg_lo:[1,0,0] neg_hi:[1,0,0]
	v_pk_fma_f32 v[222:223], v[222:223], s[16:17], v[196:197] op_sel_hi:[1,0,0] neg_lo:[1,0,0] neg_hi:[1,0,0]
	v_exp_f32_e32 v240, v242
	v_exp_f32_e32 v241, v243
	v_exp_f32_e32 v242, v244
	v_exp_f32_e32 v243, v245
	v_pk_fma_f32 v[244:245], v[248:249], s[16:17], v[196:197] op_sel_hi:[1,0,0] neg_lo:[1,0,0] neg_hi:[1,0,0]
	v_exp_f32_e32 v248, v250
	v_exp_f32_e32 v249, v251
	v_exp_f32_e32 v250, v98
	v_exp_f32_e32 v251, v99
	v_pk_mul_f32 v[98:99], v[106:107], v[100:101]
	v_pk_mul_f32 v[100:101], v[108:109], v[222:223]
	v_pk_mul_f32 v[110:111], v[106:107], v[110:111]
	v_pk_mul_f32 v[112:113], v[108:109], v[112:113]
	v_pk_mul_f32 v[246:247], v[104:105], v[104:105]
	v_exp_f32_e32 v106, v98
	v_exp_f32_e32 v107, v99
	v_exp_f32_e32 v108, v100
	v_exp_f32_e32 v109, v101
	v_pk_fma_f32 v[246:247], v[246:247], s[16:17], v[196:197] op_sel_hi:[1,0,0] neg_lo:[1,0,0] neg_hi:[1,0,0]
	v_pk_mul_f32 v[102:103], v[102:103], v[244:245]
	v_pk_mul_f32 v[104:105], v[104:105], v[246:247]
	v_exp_f32_e32 v244, v102
	v_exp_f32_e32 v245, v103
	v_exp_f32_e32 v246, v104
	v_exp_f32_e32 v247, v105
	v_pk_add_f32 v[102:103], v[240:241], 1.0 op_sel_hi:[1,0]
	v_pk_add_f32 v[104:105], v[242:243], 1.0 op_sel_hi:[1,0]
	v_pk_fma_f32 v[106:107], v[106:107], v[102:103], v[102:103]
	v_pk_fma_f32 v[108:109], v[108:109], v[104:105], v[104:105]
	v_pk_add_f32 v[240:241], v[248:249], 1.0 op_sel_hi:[1,0]
	v_pk_add_f32 v[242:243], v[250:251], 1.0 op_sel_hi:[1,0]
	s_waitcnt vmcnt(4)
	v_mov_b32_e32 v221, v220
	v_mov_b32_e32 v222, v220
	v_mov_b32_e32 v223, v220
	s_waitcnt vmcnt(3)
	s_nop 0
	v_mfma_f32_16x16x32_bf16 v[98:101], v[130:133], v[224:227], v[220:223]
	v_mfma_f32_16x16x32_bf16 v[102:105], v[134:137], v[224:227], v[220:223]
	v_rcp_f32_e32 v224, v106
	v_rcp_f32_e32 v225, v107
	v_rcp_f32_e32 v226, v108
	s_waitcnt vmcnt(2)
	v_mfma_f32_16x16x32_bf16 v[98:101], v[142:145], v[228:231], v[98:101]
	v_rcp_f32_e32 v227, v109
	v_pk_fma_f32 v[220:221], v[244:245], v[240:241], v[240:241]
	v_pk_fma_f32 v[222:223], v[246:247], v[242:243], v[242:243]
	v_mfma_f32_16x16x32_bf16 v[102:105], v[138:141], v[228:231], v[102:105]
	v_rcp_f32_e32 v220, v220
	v_rcp_f32_e32 v221, v221
	v_rcp_f32_e32 v222, v222
	s_waitcnt vmcnt(1)
	v_mfma_f32_16x16x32_bf16 v[106:109], v[150:153], v[232:235], v[98:101]
	v_rcp_f32_e32 v223, v223
	v_mad_i64_i32 v[228:229], s[26:27], v211, s61, v[198:199]
	v_mfma_f32_16x16x32_bf16 v[100:103], v[146:149], v[232:235], v[102:105]
	v_or_b32_e32 v98, 32, v210
	v_ashrrev_i32_e32 v99, 31, v98
	v_pk_mul_f32 v[234:235], v[86:87], v[86:87]
	s_waitcnt vmcnt(0)
; #define GAS __attribute__((address_space(1)))
; __device__ __forceinline__ v4u pack8(const float (&f)[8]) { v4u w; w.x = pk2(f[0], f[1]); w.y = pk2(f[2], f[3]); w.z = pk2(f[4], f[5]); w.w = pk2(f[6], f[7]); return w; }
; __device__ __forceinline__ float fexp2(float x) { return __builtin_amdgcn_exp2f(x); }
; __device__ __forceinline__ float frcp(float x) { return __builtin_amdgcn_rcpf(x); }
;     __device__ __forceinline__ void operator()(const af4 (&acc)[2][2][4][2], const pg8::Unit& u, int wr_, int wc_, int fr_, int fq_) const {
;     ...
;             for (int m = 0; m < 4; ++m) {
;                 if (ai == 0 && m == 0) load_raw(1);
;                 const int it = wr * 64 + m * 16 + fr;
;                 bf16x8 wf[4];
; #pragma unroll
;                 for (int ks = 0; ks < 4; ++ks) wf[ks] = *(const GAS bf16x8*)(wsg + (size_t)it * 128 + 32 * ks + 8 * fq);
;                 const float bsi = bs[grp * 128 + it];
;                 af4 vm[2] = {(af4){bsi, bsi, bsi, bsi}, (af4){bsi, bsi, bsi, bsi}};
; #pragma unroll
;                 for (int ks = 0; ks < 4; ++ks) {
; #pragma unroll
;                     for (int n = 0; n < 2; ++n) vm[n] = __builtin_amdgcn_mfma_f32_16x16x32_bf16(av[n][ks], wf[ks], vm[n], 0, 0, 0);
;                 }
;                 float o[8];
; #pragma unroll
;                 for (int n = 0; n < 2; ++n)
; #pragma unroll
;                     for (int e = 0; e < 4; e += 2) {
;                         const f32x2 uu = {acc[ai][0][m][n][e], acc[ai][0][m][n][e + 1]}, gg = {acc[ai][1][m][n][e], acc[ai][1][m][n][e + 1]}, vv = {vm[n][e], vm[n][e + 1]};
;                         const f32x2 ar = uu * (uu * uu * (-2.302208198f * 0.044715f) + (-2.302208198f));
;                         const f32x2 gs = gg * (-1.4426950408889634f);
;                         const f32x2 ea = {fexp2(ar.x), fexp2(ar.y)}, eb = {fexp2(gs.x), fexp2(gs.y)};
;                         const f32x2 q = eb + 1.0f, den = ea * q + q;
;                         const f32x2 r = {frcp(den.x), frcp(den.y)};
;                         const f32x2 w = (uu * gg) * vv * r;
;                         o[4 * n + e] = w.x; o[4 * n + e + 1] = w.y; }
;                 *(GAS v4u*)(Y + (size_t)(tok0 + it) * CW + chbase + 32 * wc + 8 * fq) = pack8(o);
	v_mfma_f32_16x16x32_bf16 v[104:107], v[166:169], v[236:239], v[106:109]
	v_mul_f32_e64 v240, v88, v84
	v_mul_f32_e64 v241, v89, v85
	v_pk_mul_f32 v[232:233], v[88:89], v[88:89]
	v_mfma_f32_16x16x32_bf16 v[100:103], v[162:165], v[236:239], v[100:103]
	v_lshl_add_u64 v[108:109], v[228:229], 0, s[40:41]
	v_lshl_add_u64 v[108:109], v[108:109], 0, s[6:7]
	v_lshl_add_u64 v[108:109], v[108:109], 0, v[186:187]
	s_nop 0
	v_pk_mul_f32 v[104:105], v[110:111], v[104:105]
	v_pk_mul_f32 v[106:107], v[112:113], v[106:107]
	s_nop 1
	v_pk_mul_f32 v[100:101], v[252:253], v[100:101]
	v_pk_mul_f32 v[102:103], v[192:193], v[102:103]
	v_pk_mul_f32 v[104:105], v[224:225], v[104:105]
	v_pk_mul_f32 v[106:107], v[226:227], v[106:107]
	v_pk_mul_f32 v[110:111], v[220:221], v[100:101]
	v_pk_mul_f32 v[112:113], v[222:223], v[102:103]
	v_cvt_pk_bf16_f32 v100, v104, v105
	v_cvt_pk_bf16_f32 v101, v106, v107
	v_cvt_pk_bf16_f32 v102, v110, v111
	v_pk_mul_f32 v[106:107], v[90:91], v[90:91]
	v_cvt_pk_bf16_f32 v103, v112, v113
	global_store_dwordx4 v[108:109], v[100:103], off
	global_load_dword v104, v[200:201], off offset:128
	v_pk_mul_f32 v[112:113], v[94:95], s[20:21] op_sel_hi:[1,0]
	v_lshlrev_b64 v[100:101], 8, v[98:99]
	v_lshl_add_u64 v[102:103], v[218:219], 0, v[100:101]
	global_load_dwordx4 v[108:111], v[102:103], off
	global_load_dwordx4 v[220:223], v[102:103], off offset:64
	global_load_dwordx4 v[224:227], v[102:103], off offset:128
	global_load_dwordx4 v[228:231], v[102:103], off offset:192
	v_pk_mul_f32 v[100:101], v[92:93], v[92:93]
	v_pk_mul_f32 v[192:193], v[96:97], s[20:21] op_sel_hi:[1,0]
	v_pk_mul_f32 v[236:237], v[82:83], s[20:21] op_sel_hi:[1,0]
	v_pk_mul_f32 v[238:239], v[86:87], v[82:83]
	v_pk_mul_f32 v[82:83], v[84:85], s[20:21] op_sel_hi:[1,0]
	v_pk_fma_f32 v[84:85], v[106:107], s[16:17], v[196:197] op_sel_hi:[1,0,0] neg_lo:[1,0,0] neg_hi:[1,0,0]
	v_exp_f32_e32 v106, v112
	v_exp_f32_e32 v107, v113
	v_pk_fma_f32 v[100:101], v[100:101], s[16:17], v[196:197] op_sel_hi:[1,0,0] neg_lo:[1,0,0] neg_hi:[1,0,0]
	v_exp_f32_e32 v112, v192
	v_exp_f32_e32 v113, v193
	v_pk_fma_f32 v[192:193], v[234:235], s[16:17], v[196:197] op_sel_hi:[1,0,0] neg_lo:[1,0,0] neg_hi:[1,0,0]
	v_exp_f32_e32 v234, v236
	v_exp_f32_e32 v235, v237
	v_exp_f32_e32 v236, v82
	v_exp_f32_e32 v237, v83
	v_pk_mul_f32 v[82:83], v[90:91], v[84:85]
	v_pk_mul_f32 v[84:85], v[92:93], v[100:101]
	v_pk_mul_f32 v[94:95], v[90:91], v[94:95]
	v_pk_mul_f32 v[96:97], v[92:93], v[96:97]
	v_exp_f32_e32 v90, v82
	v_exp_f32_e32 v91, v83
	v_exp_f32_e32 v92, v84
	v_exp_f32_e32 v93, v85
	v_pk_fma_f32 v[232:233], v[232:233], s[16:17], v[196:197] op_sel_hi:[1,0,0] neg_lo:[1,0,0] neg_hi:[1,0,0]
	v_pk_mul_f32 v[86:87], v[86:87], v[192:193]
	v_pk_mul_f32 v[88:89], v[88:89], v[232:233]
	v_exp_f32_e32 v100, v86
	v_exp_f32_e32 v101, v87
	v_pk_add_f32 v[86:87], v[106:107], 1.0 op_sel_hi:[1,0]
	v_exp_f32_e32 v192, v88
	v_exp_f32_e32 v193, v89
	v_pk_add_f32 v[88:89], v[112:113], 1.0 op_sel_hi:[1,0]
	v_pk_fma_f32 v[90:91], v[90:91], v[86:87], v[86:87]
	v_pk_fma_f32 v[92:93], v[92:93], v[88:89], v[88:89]
	v_pk_add_f32 v[112:113], v[234:235], 1.0 op_sel_hi:[1,0]
	v_pk_add_f32 v[232:233], v[236:237], 1.0 op_sel_hi:[1,0]
	v_pk_fma_f32 v[100:101], v[100:101], v[112:113], v[112:113]
	v_rcp_f32_e32 v90, v90
	v_rcp_f32_e32 v91, v91
	v_rcp_f32_e32 v92, v92
	v_rcp_f32_e32 v93, v93
	v_add_u32_e32 v99, s42, v98
	v_pk_mul_f32 v[112:113], v[78:79], s[20:21] op_sel_hi:[1,0]
	v_pk_mul_f32 v[78:79], v[74:75], v[78:79]
	s_waitcnt vmcnt(4)
	v_mov_b32_e32 v105, v104
	v_mov_b32_e32 v106, v104
	v_mov_b32_e32 v107, v104
	s_waitcnt vmcnt(3)
	s_nop 0
	v_mfma_f32_16x16x32_bf16 v[82:85], v[130:133], v[108:111], v[104:107]
	v_mfma_f32_16x16x32_bf16 v[86:89], v[134:137], v[108:111], v[104:107]
	v_mad_i64_i32 v[108:109], s[26:27], v99, s61, v[198:199]
	v_lshl_add_u64 v[108:109], v[108:109], 0, s[40:41]
	s_waitcnt vmcnt(2)
	v_mfma_f32_16x16x32_bf16 v[82:85], v[142:145], v[220:223], v[82:85]
	v_fma_f32 v104, v192, v232, v232
	v_fma_f32 v105, v193, v233, v233
	v_rcp_f32_e32 v106, v100
	v_rcp_f32_e32 v107, v101
	v_mfma_f32_16x16x32_bf16 v[86:89], v[138:141], v[220:223], v[86:89]
	v_rcp_f32_e32 v104, v104
	v_rcp_f32_e32 v105, v105
	v_lshl_add_u64 v[108:109], v[108:109], 0, s[6:7]
	s_waitcnt vmcnt(1)
	v_mfma_f32_16x16x32_bf16 v[82:85], v[150:153], v[224:227], v[82:85]
	v_lshl_add_u64 v[108:109], v[108:109], 0, v[186:187]
	v_or_b32_e32 v100, 48, v210
	v_ashrrev_i32_e32 v101, 31, v100
	v_mfma_f32_16x16x32_bf16 v[86:89], v[146:149], v[224:227], v[86:89]
	v_mul_f32_e64 v110, v74, v74
	v_mul_f32_e64 v111, v75, v75
	v_pk_mul_f32 v[192:193], v[80:81], s[20:21] op_sel_hi:[1,0]
	v_pk_mul_f32 v[220:221], v[70:71], v[70:71]
	s_waitcnt vmcnt(0)
;     __device__ __forceinline__ void operator()(const af4 (&acc)[2][2][4][2], const pg8::Unit& u, int wr_, int wc_, int fr_, int fq_) const {
;     ...
;             const int tok0 = u.pm * 256 + ai * 128;
;             bf16x8 av[2][4];
; #pragma unroll
;             for (int ks = 0; ks < 4; ++ks) {
;                 const int j0 = tok0 + 32 * ks + 8 * fq;
;                 f32x4 st[4];
; #pragma unroll
;                 for (int q = 0; q < 4; ++q) st[q] = *(const GAS f32x4*)(stats + (size_t)(j0 + 2 * q) * 2);
; #pragma unroll
;                 for (int n = 0; n < 2; ++n) {
;                     float vf[8];
;                     unpack8(raw[n][ks], vf);
; #pragma unroll
;     ...
;             for (int m = 0; m < 4; ++m) {
;                 if (ai == 0 && m == 0) load_raw(1);
;                 const int it = wr * 64 + m * 16 + fr;
;                 bf16x8 wf[4];
; #pragma unroll
;                 for (int ks = 0; ks < 4; ++ks) wf[ks] = *(const GAS bf16x8*)(wsg + (size_t)it * 128 + 32 * ks + 8 * fq);
;                 const float bsi = bs[grp * 128 + it];
;                 af4 vm[2] = {(af4){bsi, bsi, bsi, bsi}, (af4){bsi, bsi, bsi, bsi}};
; #pragma unroll
;                 for (int ks = 0; ks < 4; ++ks) {
; #pragma unroll
;                     for (int n = 0; n < 2; ++n) vm[n] = __builtin_amdgcn_mfma_f32_16x16x32_bf16(av[n][ks], wf[ks], vm[n], 0, 0, 0);
;                 }
;                 float o[8];
; #pragma unroll
;                 for (int n = 0; n < 2; ++n)
; #pragma unroll
;                     for (int e = 0; e < 4; e += 2) {
;                         const f32x2 uu = {acc[ai][0][m][n][e], acc[ai][0][m][n][e + 1]}, gg = {acc[ai][1][m][n][e], acc[ai][1][m][n][e + 1]}, vv = {vm[n][e], vm[n][e + 1]};
;                         const f32x2 ar = uu * (uu * uu * (-2.302208198f * 0.044715f) + (-2.302208198f));
;                         const f32x2 gs = gg * (-1.4426950408889634f);
;                         const f32x2 ea = {fexp2(ar.x), fexp2(ar.y)}, eb = {fexp2(gs.x), fexp2(gs.y)};
;                         const f32x2 q = eb + 1.0f, den = ea * q + q;
;                         const f32x2 r = {frcp(den.x), frcp(den.y)};
;                         const f32x2 w = (uu * gg) * vv * r;
;                         o[4 * n + e] = w.x; o[4 * n + e + 1] = w.y; }
;                 *(GAS v4u*)(Y + (size_t)(tok0 + it) * CW + chbase + 32 * wc + 8 * fq) = pack8(o);
	v_mfma_f32_16x16x32_bf16 v[82:85], v[166:169], v[228:231], v[82:85]
	v_mul_f32_e64 v222, v66, s20
	v_mul_f32_e64 v223, v67, s20
	v_pk_mul_f32 v[224:225], v[70:71], v[66:67]
	v_pk_mul_f32 v[66:67], v[68:69], s[20:21] op_sel_hi:[1,0]
	v_mfma_f32_16x16x32_bf16 v[86:89], v[162:165], v[228:231], v[86:89]
	v_mul_f32_e64 v226, v72, v68
	v_mul_f32_e64 v227, v73, v69
	s_nop 0
	v_pk_mul_f32 v[82:83], v[94:95], v[82:83]
	v_pk_mul_f32 v[84:85], v[96:97], v[84:85]
	v_pk_mul_f32 v[82:83], v[90:91], v[82:83]
	v_pk_mul_f32 v[84:85], v[92:93], v[84:85]
	s_nop 0
	v_pk_mul_f32 v[86:87], v[238:239], v[86:87]
	v_pk_mul_f32 v[88:89], v[240:241], v[88:89]
	v_pk_mul_f32 v[86:87], v[106:107], v[86:87]
	v_pk_mul_f32 v[88:89], v[104:105], v[88:89]
	v_cvt_pk_bf16_f32 v82, v82, v83
	v_cvt_pk_bf16_f32 v83, v84, v85
	v_cvt_pk_bf16_f32 v84, v86, v87
	v_pk_fma_f32 v[68:69], v[110:111], s[16:17], v[196:197] op_sel_hi:[1,0,0] neg_lo:[1,0,0] neg_hi:[1,0,0]
	v_cvt_pk_bf16_f32 v85, v88, v89
	global_store_dwordx4 v[108:109], v[82:85], off
	global_load_dword v82, v[200:201], off offset:192
	v_exp_f32_e32 v110, v112
	v_lshlrev_b64 v[84:85], 8, v[100:101]
	v_lshl_add_u64 v[104:105], v[218:219], 0, v[84:85]
	global_load_dwordx4 v[86:89], v[104:105], off
	global_load_dwordx4 v[90:93], v[104:105], off offset:64
	global_load_dwordx4 v[94:97], v[104:105], off offset:128
	global_load_dwordx4 v[106:109], v[104:105], off offset:192
	v_pk_mul_f32 v[84:85], v[76:77], v[76:77]
	v_pk_mul_f32 v[218:219], v[72:73], v[72:73]
	v_exp_f32_e32 v111, v113
	v_pk_fma_f32 v[84:85], v[84:85], s[16:17], v[196:197] op_sel_hi:[1,0,0] neg_lo:[1,0,0] neg_hi:[1,0,0]
	v_exp_f32_e32 v112, v192
	v_exp_f32_e32 v113, v193
	v_pk_fma_f32 v[192:193], v[220:221], s[16:17], v[196:197] op_sel_hi:[1,0,0] neg_lo:[1,0,0] neg_hi:[1,0,0]
	v_pk_fma_f32 v[218:219], v[218:219], s[16:17], v[196:197] op_sel_hi:[1,0,0] neg_lo:[1,0,0] neg_hi:[1,0,0]
	v_pk_mul_f32 v[68:69], v[74:75], v[68:69]
	v_exp_f32_e32 v220, v222
	v_exp_f32_e32 v221, v223
	v_exp_f32_e32 v66, v66
	v_exp_f32_e32 v67, v67
	v_pk_mul_f32 v[74:75], v[76:77], v[84:85]
	v_pk_mul_f32 v[70:71], v[70:71], v[192:193]
	v_pk_mul_f32 v[72:73], v[72:73], v[218:219]
	v_exp_f32_e32 v68, v68
	v_exp_f32_e32 v69, v69
	v_exp_f32_e32 v74, v74
	v_exp_f32_e32 v75, v75
	v_exp_f32_e32 v70, v70
	v_exp_f32_e32 v71, v71
	v_exp_f32_e32 v72, v72
	v_exp_f32_e32 v73, v73
	v_pk_mul_f32 v[80:81], v[76:77], v[80:81]
	v_pk_add_f32 v[76:77], v[110:111], 1.0 op_sel_hi:[1,0]
	v_pk_add_f32 v[110:111], v[112:113], 1.0 op_sel_hi:[1,0]
	v_pk_add_f32 v[112:113], v[220:221], 1.0 op_sel_hi:[1,0]
	v_pk_add_f32 v[192:193], v[66:67], 1.0 op_sel_hi:[1,0]
	v_pk_fma_f32 v[76:77], v[68:69], v[76:77], v[76:77]
	v_pk_fma_f32 v[74:75], v[74:75], v[110:111], v[110:111]
	v_pk_fma_f32 v[110:111], v[70:71], v[112:113], v[112:113]
	v_pk_fma_f32 v[112:113], v[72:73], v[192:193], v[192:193]
	v_rcp_f32_e32 v76, v76
	v_rcp_f32_e32 v77, v77
	v_rcp_f32_e32 v74, v74
	v_rcp_f32_e32 v75, v75
	v_add_u32_e32 v99, s23, v210
	s_waitcnt vmcnt(4)
	v_mov_b32_e32 v83, v82
	v_mov_b32_e32 v84, v82
	v_mov_b32_e32 v85, v82
	s_waitcnt vmcnt(3)
	s_nop 0
	v_mfma_f32_16x16x32_bf16 v[66:69], v[130:133], v[86:89], v[82:85]
	v_lshlrev_b32_e32 v130, 16, v156
	v_and_b32_e32 v131, 0xffff0000, v156
	v_lshlrev_b32_e32 v132, 16, v157
	v_mfma_f32_16x16x32_bf16 v[70:73], v[134:137], v[86:89], v[82:85]
	v_rcp_f32_e32 v86, v112
	v_rcp_f32_e32 v87, v113
	v_lshlrev_b32_e32 v112, 16, v155
	s_waitcnt vmcnt(2)
	v_mfma_f32_16x16x32_bf16 v[66:69], v[142:145], v[90:93], v[66:69]
	v_rcp_f32_e32 v84, v110
	v_rcp_f32_e32 v85, v111
	v_or_b32_e32 v82, s23, v209
	v_mfma_f32_16x16x32_bf16 v[70:73], v[138:141], v[90:93], v[70:73]
	v_add_u32_e32 v90, s42, v100
	v_mad_i64_i32 v[90:91], s[26:27], v90, s61, v[198:199]
	s_waitcnt vmcnt(1)
	v_mfma_f32_16x16x32_bf16 v[66:69], v[150:153], v[94:97], v[66:69]
	v_lshl_add_u64 v[90:91], v[90:91], 0, s[40:41]
	v_lshl_add_u64 v[90:91], v[90:91], 0, s[6:7]
	v_ashrrev_i32_e32 v83, 31, v82
	v_mfma_f32_16x16x32_bf16 v[70:73], v[146:149], v[94:97], v[70:73]
	v_lshl_add_u64 v[90:91], v[90:91], 0, v[186:187]
	v_lshl_add_u32 v88, v82, 3, s98
	v_lshlrev_b32_e32 v92, 16, v177
	s_waitcnt vmcnt(0)
	v_mfma_f32_16x16x32_bf16 v[66:69], v[166:169], v[106:109], v[66:69]
	v_and_b32_e32 v93, 0xffff0000, v177
	v_lshlrev_b32_e32 v94, 16, v170
	v_and_b32_e32 v95, 0xffff0000, v170
	v_mfma_f32_16x16x32_bf16 v[70:73], v[162:165], v[106:109], v[70:73]
	v_lshlrev_b32_e32 v96, 16, v171
	s_nop 2
	v_pk_mul_f32 v[66:67], v[78:79], v[66:67]
	v_pk_mul_f32 v[68:69], v[80:81], v[68:69]
	v_pk_mul_f32 v[66:67], v[76:77], v[66:67]
	v_pk_mul_f32 v[68:69], v[74:75], v[68:69]
	v_pk_mul_f32 v[70:71], v[224:225], v[70:71]
	v_pk_mul_f32 v[72:73], v[226:227], v[72:73]
	v_pk_mul_f32 v[70:71], v[84:85], v[70:71]
	v_pk_mul_f32 v[72:73], v[86:87], v[72:73]
	v_cvt_pk_bf16_f32 v66, v66, v67
	v_cvt_pk_bf16_f32 v67, v68, v69
	v_cvt_pk_bf16_f32 v68, v70, v71
	v_or_b32_e32 v84, 32, v82
	v_cvt_pk_bf16_f32 v69, v72, v73
	global_store_dwordx4 v[90:91], v[66:69], off
	ds_read_b128 v[66:69], v88
	s_nop 0
	ds_read_b128 v[70:73], v88 offset:16
	ds_read_b128 v[74:77], v88 offset:32
	ds_read_b128 v[78:81], v88 offset:48
	v_ashrrev_i32_e32 v85, 31, v84
	v_lshl_add_u32 v88, v84, 3, s98
	v_lshlrev_b32_e32 v84, 16, v174
	v_and_b32_e32 v85, 0xffff0000, v174
	v_lshlrev_b32_e32 v86, 16, v175
	v_and_b32_e32 v87, 0xffff0000, v175
	v_lshlrev_b32_e32 v90, 16, v176
	v_and_b32_e32 v91, 0xffff0000, v176
	v_and_b32_e32 v97, 0xffff0000, v171
	v_lshlrev_b32_e32 v106, 16, v172
	v_and_b32_e32 v107, 0xffff0000, v172
	v_lshlrev_b32_e32 v108, 16, v173
	v_and_b32_e32 v109, 0xffff0000, v173
	v_lshlrev_b32_e32 v110, 16, v154
	v_and_b32_e32 v111, 0xffff0000, v154
	v_and_b32_e32 v113, 0xffff0000, v155
	v_and_b32_e32 v133, 0xffff0000, v157
	v_pk_mul_f32 v[134:135], v[54:55], v[54:55]
	v_pk_mul_f32 v[136:137], v[50:51], s[20:21] op_sel_hi:[1,0]
	v_pk_mul_f32 v[138:139], v[54:55], v[50:51]
	v_pk_mul_f32 v[50:51], v[52:53], s[20:21] op_sel_hi:[1,0]
	v_pk_mul_f32 v[140:141], v[56:57], v[52:53]
	s_waitcnt lgkmcnt(3)
; #define GAS __attribute__((address_space(1)))
; __device__ __forceinline__ void unpack8(const v4u w, float (&f)[8]) { f[0] = bflo(w.x); f[1] = bfhi(w.x); f[2] = bflo(w.y); f[3] = bfhi(w.y); f[4] = bflo(w.z); f[5] = bfhi(w.z); f[6] = bflo(w.w); f[7] = bfhi(w.w); }
; __device__ __forceinline__ v4u pack8(const float (&f)[8]) { v4u w; w.x = pk2(f[0], f[1]); w.y = pk2(f[2], f[3]); w.z = pk2(f[4], f[5]); w.w = pk2(f[6], f[7]); return w; }
;     __device__ __forceinline__ void operator()(const af4 (&acc)[2][2][4][2], const pg8::Unit& u, int wr_, int wc_, int fr_, int fq_) const {
;     ...
;             for (int ks = 0; ks < 4; ++ks) {
;                 const int j0 = tok0 + 32 * ks + 8 * fq;
;                 f32x4 st[4];
; #pragma unroll
;                 for (int q = 0; q < 4; ++q) st[q] = *(const GAS f32x4*)(stats + (size_t)(j0 + 2 * q) * 2);
; #pragma unroll
;                 for (int n = 0; n < 2; ++n) {
;                     float vf[8];
;                     unpack8(raw[n][ks], vf);
; #pragma unroll
;                     for (int q = 0; q < 4; ++q) { f32x2 t = {vf[2 * q], vf[2 * q + 1]}; t = t * (f32x2){st[q].z, st[q].w} + (f32x2){st[q].x, st[q].y}; t = t * lg[n] + lb[n]; vf[2 * q] = t.x; vf[2 * q + 1] = t.y; }
;                     av[n][ks] = __builtin_bit_cast(bf16x8, pack8(vf));
	v_pk_fma_f32 v[84:85], v[68:69], v[84:85], v[66:67]
	s_waitcnt lgkmcnt(2)
	v_pk_fma_f32 v[86:87], v[72:73], v[86:87], v[70:71]
	s_waitcnt lgkmcnt(1)
	v_pk_fma_f32 v[90:91], v[76:77], v[90:91], v[74:75]
	s_waitcnt lgkmcnt(0)
	v_pk_fma_f32 v[92:93], v[80:81], v[92:93], v[78:79]
	v_pk_fma_f32 v[66:67], v[68:69], v[94:95], v[66:67]
	v_pk_fma_f32 v[68:69], v[72:73], v[96:97], v[70:71]
	v_pk_fma_f32 v[70:71], v[76:77], v[106:107], v[74:75]
	v_pk_fma_f32 v[72:73], v[80:81], v[108:109], v[78:79]
	v_pk_fma_f32 v[74:75], v[208:209], v[84:85], v[206:207] op_sel_hi:[0,1,0]
	v_pk_fma_f32 v[76:77], v[208:209], v[86:87], v[206:207] op_sel_hi:[0,1,0]
	v_pk_fma_f32 v[78:79], v[208:209], v[90:91], v[206:207] op_sel_hi:[0,1,0]
	v_pk_fma_f32 v[80:81], v[208:209], v[92:93], v[206:207] op_sel_hi:[0,1,0]
	v_pk_fma_f32 v[66:67], v[202:203], v[66:67], v[204:205] op_sel_hi:[0,1,0]
	v_pk_fma_f32 v[68:69], v[202:203], v[68:69], v[204:205] op_sel_hi:[0,1,0]
	v_pk_fma_f32 v[84:85], v[202:203], v[70:71], v[204:205] op_sel_hi:[0,1,0]
	v_pk_fma_f32 v[86:87], v[202:203], v[72:73], v[204:205] op_sel_hi:[0,1,0]
	v_cvt_pk_bf16_f32 v70, v74, v75
	v_cvt_pk_bf16_f32 v71, v76, v77
	v_cvt_pk_bf16_f32 v72, v78, v79
	v_cvt_pk_bf16_f32 v73, v80, v81
	v_cvt_pk_bf16_f32 v66, v66, v67
	v_cvt_pk_bf16_f32 v67, v68, v69
	v_cvt_pk_bf16_f32 v68, v84, v85
	v_cvt_pk_bf16_f32 v69, v86, v87
	ds_read_b128 v[74:77], v88
	ds_read_b128 v[78:81], v88 offset:16
	ds_read_b128 v[84:87], v88 offset:32
	s_nop 0
	ds_read_b128 v[88:91], v88 offset:48
	v_or_b32_e32 v92, 64, v82
	v_ashrrev_i32_e32 v93, 31, v92
	v_lshl_add_u32 v96, v92, 3, s98
	v_lshlrev_b32_e32 v92, 16, v158
	v_and_b32_e32 v93, 0xffff0000, v158
	v_lshlrev_b32_e32 v94, 16, v159
	v_and_b32_e32 v95, 0xffff0000, v159
	v_lshlrev_b32_e32 v106, 16, v160
	v_and_b32_e32 v107, 0xffff0000, v160
	v_lshlrev_b32_e32 v108, 16, v161
	v_and_b32_e32 v109, 0xffff0000, v161
	v_or_b32_e32 v82, 0x60, v82
	v_ashrrev_i32_e32 v83, 31, v82
	s_waitcnt lgkmcnt(3)
	v_pk_fma_f32 v[92:93], v[76:77], v[92:93], v[74:75]
	s_waitcnt lgkmcnt(2)
	v_pk_fma_f32 v[94:95], v[80:81], v[94:95], v[78:79]
	s_waitcnt lgkmcnt(1)
	v_pk_fma_f32 v[106:107], v[86:87], v[106:107], v[84:85]
	s_waitcnt lgkmcnt(0)
	v_pk_fma_f32 v[108:109], v[90:91], v[108:109], v[88:89]
	v_pk_fma_f32 v[74:75], v[76:77], v[110:111], v[74:75]
	v_pk_fma_f32 v[76:77], v[80:81], v[112:113], v[78:79]
	v_pk_fma_f32 v[78:79], v[86:87], v[130:131], v[84:85]
	v_pk_fma_f32 v[80:81], v[90:91], v[132:133], v[88:89]
	v_pk_fma_f32 v[84:85], v[208:209], v[92:93], v[206:207] op_sel_hi:[0,1,0]
	v_pk_fma_f32 v[86:87], v[208:209], v[94:95], v[206:207] op_sel_hi:[0,1,0]
	v_pk_fma_f32 v[88:89], v[208:209], v[106:107], v[206:207] op_sel_hi:[0,1,0]
	v_pk_fma_f32 v[90:91], v[208:209], v[108:109], v[206:207] op_sel_hi:[0,1,0]
	v_pk_fma_f32 v[74:75], v[202:203], v[74:75], v[204:205] op_sel_hi:[0,1,0]
	v_pk_fma_f32 v[76:77], v[202:203], v[76:77], v[204:205] op_sel_hi:[0,1,0]
	v_pk_fma_f32 v[92:93], v[202:203], v[78:79], v[204:205] op_sel_hi:[0,1,0]
	v_pk_fma_f32 v[94:95], v[202:203], v[80:81], v[204:205] op_sel_hi:[0,1,0]
	v_cvt_pk_bf16_f32 v78, v84, v85
	v_cvt_pk_bf16_f32 v79, v86, v87
	v_cvt_pk_bf16_f32 v80, v88, v89
	v_cvt_pk_bf16_f32 v81, v90, v91
	v_cvt_pk_bf16_f32 v74, v74, v75
	v_cvt_pk_bf16_f32 v75, v76, v77
	v_cvt_pk_bf16_f32 v76, v92, v93
	v_cvt_pk_bf16_f32 v77, v94, v95
	ds_read_b128 v[84:87], v96
	ds_read_b128 v[88:91], v96 offset:16
	ds_read_b128 v[92:95], v96 offset:32
	ds_read_b128 v[106:109], v96 offset:48
	v_lshl_add_u32 v110, v82, 3, s98
	v_lshlrev_b32_e32 v82, 16, v126
	v_and_b32_e32 v83, 0xffff0000, v126
	v_lshlrev_b32_e32 v96, 16, v127
	v_and_b32_e32 v97, 0xffff0000, v127
	v_lshlrev_b32_e32 v112, 16, v128
	v_and_b32_e32 v113, 0xffff0000, v128
	v_lshlrev_b32_e32 v126, 16, v129
	v_and_b32_e32 v127, 0xffff0000, v129
	v_lshlrev_b32_e32 v128, 16, v122
	v_and_b32_e32 v129, 0xffff0000, v122
	v_lshlrev_b32_e32 v122, 16, v123
	v_and_b32_e32 v123, 0xffff0000, v123
	v_lshlrev_b32_e32 v130, 16, v124
	v_and_b32_e32 v131, 0xffff0000, v124
	v_lshlrev_b32_e32 v124, 16, v125
	v_and_b32_e32 v125, 0xffff0000, v125
	v_pk_mul_f32 v[132:133], v[56:57], v[56:57]
	s_waitcnt lgkmcnt(3)
	v_pk_fma_f32 v[82:83], v[86:87], v[82:83], v[84:85]
	s_waitcnt lgkmcnt(2)
	v_pk_fma_f32 v[96:97], v[90:91], v[96:97], v[88:89]
	s_waitcnt lgkmcnt(1)
	v_pk_fma_f32 v[112:113], v[94:95], v[112:113], v[92:93]
	s_waitcnt lgkmcnt(0)
	v_pk_fma_f32 v[126:127], v[108:109], v[126:127], v[106:107]
	v_pk_fma_f32 v[84:85], v[86:87], v[128:129], v[84:85]
	v_pk_fma_f32 v[86:87], v[90:91], v[122:123], v[88:89]
	v_pk_fma_f32 v[88:89], v[94:95], v[130:131], v[92:93]
	v_pk_fma_f32 v[90:91], v[108:109], v[124:125], v[106:107]
	v_pk_fma_f32 v[82:83], v[208:209], v[82:83], v[206:207] op_sel_hi:[0,1,0]
	v_pk_fma_f32 v[92:93], v[208:209], v[96:97], v[206:207] op_sel_hi:[0,1,0]
	v_pk_fma_f32 v[94:95], v[208:209], v[112:113], v[206:207] op_sel_hi:[0,1,0]
	v_pk_fma_f32 v[96:97], v[208:209], v[126:127], v[206:207] op_sel_hi:[0,1,0]
	v_pk_fma_f32 v[84:85], v[202:203], v[84:85], v[204:205] op_sel_hi:[0,1,0]
	v_pk_fma_f32 v[106:107], v[202:203], v[86:87], v[204:205] op_sel_hi:[0,1,0]
	v_pk_fma_f32 v[108:109], v[202:203], v[88:89], v[204:205] op_sel_hi:[0,1,0]
	v_pk_fma_f32 v[90:91], v[202:203], v[90:91], v[204:205] op_sel_hi:[0,1,0]
	v_cvt_pk_bf16_f32 v86, v82, v83
	v_cvt_pk_bf16_f32 v87, v92, v93
	v_cvt_pk_bf16_f32 v88, v94, v95
	v_cvt_pk_bf16_f32 v89, v96, v97
	v_cvt_pk_bf16_f32 v82, v84, v85
	v_cvt_pk_bf16_f32 v83, v106, v107
	v_cvt_pk_bf16_f32 v84, v108, v109
	v_cvt_pk_bf16_f32 v85, v90, v91
	ds_read_b128 v[90:93], v110
	ds_read_b128 v[94:97], v110 offset:16
	ds_read_b128 v[106:109], v110 offset:32
	s_nop 0
	ds_read_b128 v[110:113], v110 offset:48
	v_lshlrev_b32_e32 v122, 16, v118
	v_and_b32_e32 v123, 0xffff0000, v118
	v_lshlrev_b32_e32 v118, 16, v119
	v_and_b32_e32 v119, 0xffff0000, v119
	v_lshlrev_b32_e32 v124, 16, v120
	v_and_b32_e32 v125, 0xffff0000, v120
	v_lshlrev_b32_e32 v120, 16, v121
	v_and_b32_e32 v121, 0xffff0000, v121
	v_lshlrev_b32_e32 v126, 16, v114
	v_and_b32_e32 v127, 0xffff0000, v114
	v_lshlrev_b32_e32 v114, 16, v115
	v_and_b32_e32 v115, 0xffff0000, v115
	v_lshlrev_b32_e32 v128, 16, v116
	v_and_b32_e32 v129, 0xffff0000, v116
	v_lshlrev_b32_e32 v116, 16, v117
	v_and_b32_e32 v117, 0xffff0000, v117
	v_pk_mul_f32 v[130:131], v[64:65], s[20:21] op_sel_hi:[1,0]
	v_pk_fma_f32 v[132:133], v[132:133], s[16:17], v[196:197] op_sel_hi:[1,0,0] neg_lo:[1,0,0] neg_hi:[1,0,0]
	v_pk_mul_f32 v[64:65], v[60:61], v[64:65]
	v_pk_mul_f32 v[56:57], v[56:57], v[132:133]
	s_waitcnt lgkmcnt(3)
; #define GAS __attribute__((address_space(1)))
; __device__ __forceinline__ v4u pack8(const float (&f)[8]) { v4u w; w.x = pk2(f[0], f[1]); w.y = pk2(f[2], f[3]); w.z = pk2(f[4], f[5]); w.w = pk2(f[6], f[7]); return w; }
; __device__ __forceinline__ float fexp2(float x) { return __builtin_amdgcn_exp2f(x); }
; __device__ __forceinline__ float frcp(float x) { return __builtin_amdgcn_rcpf(x); }
;     __device__ __forceinline__ void operator()(const af4 (&acc)[2][2][4][2], const pg8::Unit& u, int wr_, int wc_, int fr_, int fq_) const {
;     ...
;             for (int m = 0; m < 4; ++m) {
;                 if (ai == 0 && m == 0) load_raw(1);
;                 const int it = wr * 64 + m * 16 + fr;
;                 bf16x8 wf[4];
; #pragma unroll
;                 for (int ks = 0; ks < 4; ++ks) wf[ks] = *(const GAS bf16x8*)(wsg + (size_t)it * 128 + 32 * ks + 8 * fq);
;                 const float bsi = bs[grp * 128 + it];
;                 af4 vm[2] = {(af4){bsi, bsi, bsi, bsi}, (af4){bsi, bsi, bsi, bsi}};
; #pragma unroll
;                 for (int ks = 0; ks < 4; ++ks) {
; #pragma unroll
;                     for (int n = 0; n < 2; ++n) vm[n] = __builtin_amdgcn_mfma_f32_16x16x32_bf16(av[n][ks], wf[ks], vm[n], 0, 0, 0);
;                 }
;                 float o[8];
; #pragma unroll
;                 for (int n = 0; n < 2; ++n)
; #pragma unroll
;                     for (int e = 0; e < 4; e += 2) {
;                         const f32x2 uu = {acc[ai][0][m][n][e], acc[ai][0][m][n][e + 1]}, gg = {acc[ai][1][m][n][e], acc[ai][1][m][n][e + 1]}, vv = {vm[n][e], vm[n][e + 1]};
;                         const f32x2 ar = uu * (uu * uu * (-2.302208198f * 0.044715f) + (-2.302208198f));
;                         const f32x2 gs = gg * (-1.4426950408889634f);
;                         const f32x2 ea = {fexp2(ar.x), fexp2(ar.y)}, eb = {fexp2(gs.x), fexp2(gs.y)};
;                         const f32x2 q = eb + 1.0f, den = ea * q + q;
;                         const f32x2 r = {frcp(den.x), frcp(den.y)};
;                         const f32x2 w = (uu * gg) * vv * r;
;                         o[4 * n + e] = w.x; o[4 * n + e + 1] = w.y; }
;                 *(GAS v4u*)(Y + (size_t)(tok0 + it) * CW + chbase + 32 * wc + 8 * fq) = pack8(o);
	v_pk_fma_f32 v[122:123], v[92:93], v[122:123], v[90:91]
	s_waitcnt lgkmcnt(2)
	v_pk_fma_f32 v[118:119], v[96:97], v[118:119], v[94:95]
	s_waitcnt lgkmcnt(1)
	v_pk_fma_f32 v[124:125], v[108:109], v[124:125], v[106:107]
	s_waitcnt lgkmcnt(0)
	v_pk_fma_f32 v[120:121], v[112:113], v[120:121], v[110:111]
	v_pk_fma_f32 v[90:91], v[92:93], v[126:127], v[90:91]
	v_pk_fma_f32 v[92:93], v[96:97], v[114:115], v[94:95]
	v_pk_fma_f32 v[94:95], v[108:109], v[128:129], v[106:107]
	v_pk_fma_f32 v[96:97], v[112:113], v[116:117], v[110:111]
	v_pk_fma_f32 v[106:107], v[208:209], v[122:123], v[206:207] op_sel_hi:[0,1,0]
	v_pk_fma_f32 v[108:109], v[208:209], v[118:119], v[206:207] op_sel_hi:[0,1,0]
	v_pk_fma_f32 v[110:111], v[208:209], v[124:125], v[206:207] op_sel_hi:[0,1,0]
	v_pk_fma_f32 v[112:113], v[208:209], v[120:121], v[206:207] op_sel_hi:[0,1,0]
	v_pk_fma_f32 v[114:115], v[202:203], v[90:91], v[204:205] op_sel_hi:[0,1,0]
	v_pk_fma_f32 v[116:117], v[202:203], v[92:93], v[204:205] op_sel_hi:[0,1,0]
	v_pk_fma_f32 v[118:119], v[202:203], v[94:95], v[204:205] op_sel_hi:[0,1,0]
	v_pk_fma_f32 v[120:121], v[202:203], v[96:97], v[204:205] op_sel_hi:[0,1,0]
	v_cvt_pk_bf16_f32 v90, v106, v107
	v_cvt_pk_bf16_f32 v91, v108, v109
	v_cvt_pk_bf16_f32 v92, v110, v111
	v_cvt_pk_bf16_f32 v93, v112, v113
	v_cvt_pk_bf16_f32 v94, v114, v115
	v_cvt_pk_bf16_f32 v95, v116, v117
	v_cvt_pk_bf16_f32 v96, v118, v119
	v_cvt_pk_bf16_f32 v97, v120, v121
	global_load_dword v106, v[200:201], off
	global_load_dwordx4 v[110:113], v[214:215], off
	global_load_dwordx4 v[114:117], v[214:215], off offset:64
	global_load_dwordx4 v[118:121], v[214:215], off offset:128
	global_load_dwordx4 v[122:125], v[214:215], off offset:192
	v_pk_mul_f32 v[108:109], v[60:61], v[60:61]
	v_pk_mul_f32 v[126:127], v[58:59], v[58:59]
	v_pk_mul_f32 v[128:129], v[62:63], s[20:21] op_sel_hi:[1,0]
	v_pk_fma_f32 v[52:53], v[126:127], s[16:17], v[196:197] op_sel_hi:[1,0,0] neg_lo:[1,0,0] neg_hi:[1,0,0]
	v_pk_fma_f32 v[108:109], v[108:109], s[16:17], v[196:197] op_sel_hi:[1,0,0] neg_lo:[1,0,0] neg_hi:[1,0,0]
	v_exp_f32_e32 v126, v128
	v_exp_f32_e32 v127, v129
	v_exp_f32_e32 v128, v130
	v_exp_f32_e32 v129, v131
	v_pk_fma_f32 v[130:131], v[134:135], s[16:17], v[196:197] op_sel_hi:[1,0,0] neg_lo:[1,0,0] neg_hi:[1,0,0]
	v_exp_f32_e32 v134, v136
	v_exp_f32_e32 v135, v137
	v_exp_f32_e32 v136, v50
	v_exp_f32_e32 v137, v51
	v_pk_mul_f32 v[50:51], v[58:59], v[52:53]
	v_pk_mul_f32 v[52:53], v[60:61], v[108:109]
	v_pk_mul_f32 v[62:63], v[58:59], v[62:63]
	v_pk_mul_f32 v[54:55], v[54:55], v[130:131]
	v_exp_f32_e32 v58, v50
	v_exp_f32_e32 v59, v51
	v_exp_f32_e32 v60, v52
	v_exp_f32_e32 v61, v53
	v_exp_f32_e32 v130, v54
	v_exp_f32_e32 v131, v55
	v_exp_f32_e32 v132, v56
	v_exp_f32_e32 v133, v57
	v_pk_add_f32 v[126:127], v[126:127], 1.0 op_sel_hi:[1,0]
	v_pk_add_f32 v[128:129], v[128:129], 1.0 op_sel_hi:[1,0]
	v_pk_add_f32 v[134:135], v[134:135], 1.0 op_sel_hi:[1,0]
	v_pk_add_f32 v[136:137], v[136:137], 1.0 op_sel_hi:[1,0]
	v_pk_fma_f32 v[58:59], v[58:59], v[126:127], v[126:127]
	v_pk_fma_f32 v[60:61], v[60:61], v[128:129], v[128:129]
	v_rcp_f32_e32 v58, v58
	v_rcp_f32_e32 v59, v59
	v_rcp_f32_e32 v60, v60
	v_rcp_f32_e32 v61, v61
	s_waitcnt vmcnt(4)
	v_mov_b32_e32 v107, v106
	v_mov_b32_e32 v108, v106
	v_mov_b32_e32 v109, v106
	s_waitcnt vmcnt(3)
	s_nop 0
	v_mfma_f32_16x16x32_bf16 v[50:53], v[70:73], v[110:113], v[106:109]
	v_mfma_f32_16x16x32_bf16 v[54:57], v[66:69], v[110:113], v[106:109]
	v_mad_i64_i32 v[110:111], s[26:27], v99, s61, v[198:199]
	v_lshl_add_u64 v[110:111], v[110:111], 0, s[40:41]
	s_waitcnt vmcnt(2)
	v_mfma_f32_16x16x32_bf16 v[50:53], v[78:81], v[114:117], v[50:53]
	v_fma_f32 v106, v130, v134, v134
	v_fma_f32 v107, v131, v135, v135
	v_pk_fma_f32 v[108:109], v[132:133], v[136:137], v[136:137]
	v_rcp_f32_e32 v106, v106
	v_mfma_f32_16x16x32_bf16 v[54:57], v[74:77], v[114:117], v[54:57]
	v_rcp_f32_e32 v107, v107
	v_rcp_f32_e32 v108, v108
	v_rcp_f32_e32 v109, v109
	s_waitcnt vmcnt(1)
	v_mfma_f32_16x16x32_bf16 v[50:53], v[86:89], v[118:121], v[50:53]
	v_lshl_add_u64 v[110:111], v[110:111], 0, s[6:7]
	v_lshl_add_u64 v[110:111], v[110:111], 0, v[186:187]
	v_pk_mul_f32 v[112:113], v[46:47], s[20:21] op_sel_hi:[1,0]
	v_mfma_f32_16x16x32_bf16 v[54:57], v[82:85], v[118:121], v[54:57]
	v_mul_f32_e64 v114, v48, s20
	v_mul_f32_e64 v115, v49, s20
	v_pk_mul_f32 v[116:117], v[40:41], v[40:41]
	v_pk_mul_f32 v[118:119], v[38:39], v[38:39]
	s_waitcnt vmcnt(0)
; #define GAS __attribute__((address_space(1)))
; __device__ __forceinline__ v4u pack8(const float (&f)[8]) { v4u w; w.x = pk2(f[0], f[1]); w.y = pk2(f[2], f[3]); w.z = pk2(f[4], f[5]); w.w = pk2(f[6], f[7]); return w; }
; __device__ __forceinline__ float fexp2(float x) { return __builtin_amdgcn_exp2f(x); }
; __device__ __forceinline__ float frcp(float x) { return __builtin_amdgcn_rcpf(x); }
;     __device__ __forceinline__ void operator()(const af4 (&acc)[2][2][4][2], const pg8::Unit& u, int wr_, int wc_, int fr_, int fq_) const {
;     ...
;             for (int m = 0; m < 4; ++m) {
;                 if (ai == 0 && m == 0) load_raw(1);
;                 const int it = wr * 64 + m * 16 + fr;
;                 bf16x8 wf[4];
; #pragma unroll
;                 for (int ks = 0; ks < 4; ++ks) wf[ks] = *(const GAS bf16x8*)(wsg + (size_t)it * 128 + 32 * ks + 8 * fq);
;                 const float bsi = bs[grp * 128 + it];
;                 af4 vm[2] = {(af4){bsi, bsi, bsi, bsi}, (af4){bsi, bsi, bsi, bsi}};
; #pragma unroll
;                 for (int ks = 0; ks < 4; ++ks) {
; #pragma unroll
;                     for (int n = 0; n < 2; ++n) vm[n] = __builtin_amdgcn_mfma_f32_16x16x32_bf16(av[n][ks], wf[ks], vm[n], 0, 0, 0);
;                 }
;                 float o[8];
; #pragma unroll
;                 for (int n = 0; n < 2; ++n)
; #pragma unroll
;                     for (int e = 0; e < 4; e += 2) {
;                         const f32x2 uu = {acc[ai][0][m][n][e], acc[ai][0][m][n][e + 1]}, gg = {acc[ai][1][m][n][e], acc[ai][1][m][n][e + 1]}, vv = {vm[n][e], vm[n][e + 1]};
;                         const f32x2 ar = uu * (uu * uu * (-2.302208198f * 0.044715f) + (-2.302208198f));
;                         const f32x2 gs = gg * (-1.4426950408889634f);
;                         const f32x2 ea = {fexp2(ar.x), fexp2(ar.y)}, eb = {fexp2(gs.x), fexp2(gs.y)};
;                         const f32x2 q = eb + 1.0f, den = ea * q + q;
;                         const f32x2 r = {frcp(den.x), frcp(den.y)};
;                         const f32x2 w = (uu * gg) * vv * r;
;                         o[4 * n + e] = w.x; o[4 * n + e + 1] = w.y; }
;                 *(GAS v4u*)(Y + (size_t)(tok0 + it) * CW + chbase + 32 * wc + 8 * fq) = pack8(o);
	v_mfma_f32_16x16x32_bf16 v[50:53], v[90:93], v[122:125], v[50:53]
	v_mul_f32_e64 v120, v34, s20
	v_mul_f32_e64 v121, v35, s20
	v_pk_fma_f32 v[116:117], v[116:117], s[16:17], v[196:197] op_sel_hi:[1,0,0] neg_lo:[1,0,0] neg_hi:[1,0,0]
	v_pk_mul_f32 v[46:47], v[42:43], v[46:47]
	v_mfma_f32_16x16x32_bf16 v[54:57], v[94:97], v[122:125], v[54:57]
	v_mul_f32_e64 v122, v38, v34
	v_mul_f32_e64 v123, v39, v35
	s_nop 0
	v_pk_mul_f32 v[50:51], v[62:63], v[50:51]
	v_pk_mul_f32 v[52:53], v[64:65], v[52:53]
	v_pk_mul_f32 v[50:51], v[58:59], v[50:51]
	v_pk_mul_f32 v[52:53], v[60:61], v[52:53]
	s_nop 0
	v_pk_mul_f32 v[54:55], v[138:139], v[54:55]
	v_pk_mul_f32 v[56:57], v[140:141], v[56:57]
	v_pk_mul_f32 v[54:55], v[106:107], v[54:55]
	v_pk_mul_f32 v[56:57], v[108:109], v[56:57]
	v_cvt_pk_bf16_f32 v50, v50, v51
	v_cvt_pk_bf16_f32 v51, v52, v53
	v_cvt_pk_bf16_f32 v52, v54, v55
	v_pk_mul_f32 v[34:35], v[36:37], s[20:21] op_sel_hi:[1,0]
	v_cvt_pk_bf16_f32 v53, v56, v57
	global_store_dwordx4 v[110:111], v[50:53], off
	global_load_dword v50, v[200:201], off offset:64
	s_nop 0
	global_load_dwordx4 v[54:57], v[216:217], off
	global_load_dwordx4 v[58:61], v[216:217], off offset:64
	global_load_dwordx4 v[62:65], v[216:217], off offset:128
	global_load_dwordx4 v[106:109], v[216:217], off offset:192
	v_pk_mul_f32 v[52:53], v[44:45], v[44:45]
	v_pk_mul_f32 v[110:111], v[42:43], v[42:43]
	v_pk_mul_f32 v[124:125], v[40:41], v[36:37]
	v_pk_fma_f32 v[36:37], v[110:111], s[16:17], v[196:197] op_sel_hi:[1,0,0] neg_lo:[1,0,0] neg_hi:[1,0,0]
	v_pk_fma_f32 v[52:53], v[52:53], s[16:17], v[196:197] op_sel_hi:[1,0,0] neg_lo:[1,0,0] neg_hi:[1,0,0]
	v_exp_f32_e32 v110, v112
	v_exp_f32_e32 v111, v113
	v_exp_f32_e32 v112, v114
	v_exp_f32_e32 v113, v115
	v_pk_fma_f32 v[114:115], v[118:119], s[16:17], v[196:197] op_sel_hi:[1,0,0] neg_lo:[1,0,0] neg_hi:[1,0,0]
	v_exp_f32_e32 v118, v120
	v_exp_f32_e32 v119, v121
	v_exp_f32_e32 v120, v34
	v_exp_f32_e32 v121, v35
	v_pk_mul_f32 v[34:35], v[42:43], v[36:37]
	v_pk_mul_f32 v[36:37], v[44:45], v[52:53]
	v_pk_mul_f32 v[48:49], v[44:45], v[48:49]
	v_pk_mul_f32 v[38:39], v[38:39], v[114:115]
	v_pk_mul_f32 v[40:41], v[40:41], v[116:117]
	v_exp_f32_e32 v42, v34
	v_exp_f32_e32 v43, v35
	v_exp_f32_e32 v44, v36
	v_exp_f32_e32 v45, v37
	v_exp_f32_e32 v114, v38
	v_exp_f32_e32 v115, v39
	v_exp_f32_e32 v116, v40
	v_exp_f32_e32 v117, v41
	v_pk_add_f32 v[110:111], v[110:111], 1.0 op_sel_hi:[1,0]
	v_pk_add_f32 v[112:113], v[112:113], 1.0 op_sel_hi:[1,0]
	v_pk_add_f32 v[118:119], v[118:119], 1.0 op_sel_hi:[1,0]
	v_pk_add_f32 v[120:121], v[120:121], 1.0 op_sel_hi:[1,0]
	v_pk_fma_f32 v[42:43], v[42:43], v[110:111], v[110:111]
	v_pk_fma_f32 v[44:45], v[44:45], v[112:113], v[112:113]
	v_rcp_f32_e32 v42, v42
	v_rcp_f32_e32 v43, v43
	v_rcp_f32_e32 v44, v44
	v_rcp_f32_e32 v45, v45
	s_waitcnt vmcnt(4)
	v_mov_b32_e32 v51, v50
	v_mov_b32_e32 v52, v50
	v_mov_b32_e32 v53, v50
	s_waitcnt vmcnt(3)
	s_nop 0
	v_mfma_f32_16x16x32_bf16 v[34:37], v[70:73], v[54:57], v[50:53]
	v_mfma_f32_16x16x32_bf16 v[38:41], v[66:69], v[54:57], v[50:53]
	v_add_u32_e32 v54, s23, v212
	v_mad_i64_i32 v[54:55], s[26:27], v54, s61, v[198:199]
	s_waitcnt vmcnt(2)
	v_mfma_f32_16x16x32_bf16 v[34:37], v[78:81], v[58:61], v[34:37]
	v_fma_f32 v50, v114, v118, v118
	v_fma_f32 v51, v115, v119, v119
	v_pk_fma_f32 v[52:53], v[116:117], v[120:121], v[120:121]
	v_rcp_f32_e32 v50, v50
	v_mfma_f32_16x16x32_bf16 v[38:41], v[74:77], v[58:61], v[38:41]
	v_rcp_f32_e32 v51, v51
	v_rcp_f32_e32 v52, v52
	v_rcp_f32_e32 v53, v53
	s_waitcnt vmcnt(1)
	v_mfma_f32_16x16x32_bf16 v[34:37], v[86:89], v[62:65], v[34:37]
	v_lshl_add_u64 v[54:55], v[54:55], 0, s[40:41]
	v_lshl_add_u64 v[54:55], v[54:55], 0, s[6:7]
	v_lshl_add_u64 v[54:55], v[54:55], 0, v[186:187]
	v_mfma_f32_16x16x32_bf16 v[38:41], v[82:85], v[62:65], v[38:41]
	v_mul_f32_e64 v56, v30, s20
	v_mul_f32_e64 v57, v31, s20
	v_pk_mul_f32 v[58:59], v[32:33], s[20:21] op_sel_hi:[1,0]
	v_pk_mul_f32 v[60:61], v[24:25], v[24:25]
	s_waitcnt vmcnt(0)
	v_mfma_f32_16x16x32_bf16 v[34:37], v[90:93], v[106:109], v[34:37]
	v_mul_f32_e64 v62, v22, v22
	v_mul_f32_e64 v63, v23, v23
	v_pk_mul_f32 v[64:65], v[18:19], s[20:21] op_sel_hi:[1,0]
	v_pk_fma_f32 v[60:61], v[60:61], s[16:17], v[196:197] op_sel_hi:[1,0,0] neg_lo:[1,0,0] neg_hi:[1,0,0]
	v_mfma_f32_16x16x32_bf16 v[38:41], v[94:97], v[106:109], v[38:41]
	v_mul_f32_e64 v106, v24, v20
	v_mul_f32_e64 v107, v25, v21
	s_nop 0
	v_pk_mul_f32 v[34:35], v[46:47], v[34:35]
	v_pk_mul_f32 v[36:37], v[48:49], v[36:37]
	v_pk_mul_f32 v[34:35], v[42:43], v[34:35]
	v_pk_mul_f32 v[36:37], v[44:45], v[36:37]
	s_nop 0
	v_pk_mul_f32 v[38:39], v[122:123], v[38:39]
	v_pk_mul_f32 v[40:41], v[124:125], v[40:41]
	v_pk_mul_f32 v[38:39], v[50:51], v[38:39]
	v_pk_mul_f32 v[40:41], v[52:53], v[40:41]
	v_cvt_pk_bf16_f32 v34, v34, v35
	v_cvt_pk_bf16_f32 v35, v36, v37
	v_cvt_pk_bf16_f32 v36, v38, v39
	v_pk_mul_f32 v[30:31], v[26:27], v[30:31]
	v_cvt_pk_bf16_f32 v37, v40, v41
	global_store_dwordx4 v[54:55], v[34:37], off
	global_load_dword v34, v[200:201], off offset:128
	s_nop 0
	global_load_dwordx4 v[38:41], v[102:103], off
	global_load_dwordx4 v[42:45], v[102:103], off offset:64
	global_load_dwordx4 v[46:49], v[102:103], off offset:128
	global_load_dwordx4 v[50:53], v[102:103], off offset:192
	v_pk_mul_f32 v[36:37], v[28:29], v[28:29]
	v_pk_mul_f32 v[54:55], v[26:27], v[26:27]
	v_pk_mul_f32 v[102:103], v[22:23], v[18:19]
	v_pk_mul_f32 v[18:19], v[20:21], s[20:21] op_sel_hi:[1,0]
	v_pk_fma_f32 v[20:21], v[54:55], s[16:17], v[196:197] op_sel_hi:[1,0,0] neg_lo:[1,0,0] neg_hi:[1,0,0]
	v_pk_fma_f32 v[36:37], v[36:37], s[16:17], v[196:197] op_sel_hi:[1,0,0] neg_lo:[1,0,0] neg_hi:[1,0,0]
	v_exp_f32_e32 v54, v56
	v_exp_f32_e32 v55, v57
	v_exp_f32_e32 v56, v58
	v_exp_f32_e32 v57, v59
	v_pk_fma_f32 v[58:59], v[62:63], s[16:17], v[196:197] op_sel_hi:[1,0,0] neg_lo:[1,0,0] neg_hi:[1,0,0]
	v_exp_f32_e32 v62, v64
	v_exp_f32_e32 v63, v65
	v_exp_f32_e32 v64, v18
	v_exp_f32_e32 v65, v19
	v_pk_mul_f32 v[18:19], v[26:27], v[20:21]
	v_pk_mul_f32 v[20:21], v[28:29], v[36:37]
	v_pk_mul_f32 v[32:33], v[28:29], v[32:33]
	v_pk_mul_f32 v[22:23], v[22:23], v[58:59]
	v_pk_mul_f32 v[24:25], v[24:25], v[60:61]
	v_exp_f32_e32 v26, v18
	v_exp_f32_e32 v27, v19
	v_exp_f32_e32 v28, v20
	v_exp_f32_e32 v29, v21
	v_exp_f32_e32 v58, v22
	v_exp_f32_e32 v59, v23
	v_exp_f32_e32 v60, v24
	v_exp_f32_e32 v61, v25
	v_pk_add_f32 v[54:55], v[54:55], 1.0 op_sel_hi:[1,0]
	v_pk_add_f32 v[56:57], v[56:57], 1.0 op_sel_hi:[1,0]
	v_pk_add_f32 v[62:63], v[62:63], 1.0 op_sel_hi:[1,0]
	v_pk_add_f32 v[64:65], v[64:65], 1.0 op_sel_hi:[1,0]
	v_pk_fma_f32 v[26:27], v[26:27], v[54:55], v[54:55]
	v_pk_fma_f32 v[28:29], v[28:29], v[56:57], v[56:57]
	v_rcp_f32_e32 v26, v26
	v_rcp_f32_e32 v27, v27
	v_rcp_f32_e32 v28, v28
	v_rcp_f32_e32 v29, v29
	s_waitcnt vmcnt(4)
; template <class Epi, class Sched, bool ALIGN_EPI = false, bool SP2 = false>
; __device__ __forceinline__ void gemm_phase(PG8_LAS unsigned char* lds, const Gemm g, const Sched& S, const Epi& E) {
;     ...
;         if constexpr (ALIGN_EPI) { if (wr == 0) PG8_BAR; }
;         E(acc, cur, wr, wc, fr, fq);
;         if (!has_next) break;
; #pragma unroll
;         for (int a = 0; a < 2; ++a)
; #pragma unroll
;             for (int b = 0; b < 2; ++b)
; #pragma unroll
;                 for (int m = 0; m < 4; ++m)
; #pragma unroll
;     __device__ __forceinline__ void operator()(const af4 (&acc)[2][2][4][2], const pg8::Unit& u, int wr_, int wc_, int fr_, int fq_) const {
;     ...
;             for (int m = 0; m < 4; ++m) {
;                 if (ai == 0 && m == 0) load_raw(1);
;                 const int it = wr * 64 + m * 16 + fr;
;                 bf16x8 wf[4];
; #pragma unroll
;                 for (int ks = 0; ks < 4; ++ks) wf[ks] = *(const GAS bf16x8*)(wsg + (size_t)it * 128 + 32 * ks + 8 * fq);
;                 const float bsi = bs[grp * 128 + it];
;                 af4 vm[2] = {(af4){bsi, bsi, bsi, bsi}, (af4){bsi, bsi, bsi, bsi}};
; #pragma unroll
;                 for (int ks = 0; ks < 4; ++ks) {
; #pragma unroll
;                     for (int n = 0; n < 2; ++n) vm[n] = __builtin_amdgcn_mfma_f32_16x16x32_bf16(av[n][ks], wf[ks], vm[n], 0, 0, 0);
;                 }
;                 float o[8];
; #pragma unroll
;                 for (int n = 0; n < 2; ++n)
; #pragma unroll
;                     for (int e = 0; e < 4; e += 2) {
;                         const f32x2 uu = {acc[ai][0][m][n][e], acc[ai][0][m][n][e + 1]}, gg = {acc[ai][1][m][n][e], acc[ai][1][m][n][e + 1]}, vv = {vm[n][e], vm[n][e + 1]};
;                         const f32x2 ar = uu * (uu * uu * (-2.302208198f * 0.044715f) + (-2.302208198f));
;                         const f32x2 gs = gg * (-1.4426950408889634f);
;                         const f32x2 ea = {fexp2(ar.x), fexp2(ar.y)}, eb = {fexp2(gs.x), fexp2(gs.y)};
;                         const f32x2 q = eb + 1.0f, den = ea * q + q;
;                         const f32x2 r = {frcp(den.x), frcp(den.y)};
;                         const f32x2 w = (uu * gg) * vv * r;
;                         o[4 * n + e] = w.x; o[4 * n + e + 1] = w.y; }
;                 *(GAS v4u*)(Y + (size_t)(tok0 + it) * CW + chbase + 32 * wc + 8 * fq) = pack8(o);
	v_mov_b32_e32 v35, v34
	v_mov_b32_e32 v36, v34
	v_mov_b32_e32 v37, v34
	s_waitcnt vmcnt(3)
	s_nop 0
	v_mfma_f32_16x16x32_bf16 v[18:21], v[70:73], v[38:41], v[34:37]
	v_mfma_f32_16x16x32_bf16 v[22:25], v[66:69], v[38:41], v[34:37]
	v_add_u32_e32 v38, s23, v98
	v_mad_i64_i32 v[38:39], s[26:27], v38, s61, v[198:199]
	s_waitcnt vmcnt(2)
	v_mfma_f32_16x16x32_bf16 v[18:21], v[78:81], v[42:45], v[18:21]
	v_fma_f32 v34, v58, v62, v62
	v_fma_f32 v35, v59, v63, v63
	v_pk_fma_f32 v[36:37], v[60:61], v[64:65], v[64:65]
	v_rcp_f32_e32 v34, v34
	v_mfma_f32_16x16x32_bf16 v[22:25], v[74:77], v[42:45], v[22:25]
	v_rcp_f32_e32 v35, v35
	v_rcp_f32_e32 v36, v36
	v_rcp_f32_e32 v37, v37
	s_waitcnt vmcnt(1)
	v_mfma_f32_16x16x32_bf16 v[18:21], v[86:89], v[46:49], v[18:21]
	v_lshl_add_u64 v[38:39], v[38:39], 0, s[40:41]
	v_lshl_add_u64 v[38:39], v[38:39], 0, s[6:7]
	v_lshl_add_u64 v[38:39], v[38:39], 0, v[186:187]
	v_mfma_f32_16x16x32_bf16 v[22:25], v[82:85], v[46:49], v[22:25]
	v_mul_f32_e64 v40, v14, s20
	v_mul_f32_e64 v41, v15, s20
	v_pk_mul_f32 v[42:43], v[16:17], s[20:21] op_sel_hi:[1,0]
	v_pk_mul_f32 v[44:45], v[8:9], v[8:9]
	s_waitcnt vmcnt(0)
	v_mfma_f32_16x16x32_bf16 v[18:21], v[90:93], v[50:53], v[18:21]
	v_mul_f32_e64 v46, v6, v6
	v_mul_f32_e64 v47, v7, v7
	v_pk_mul_f32 v[48:49], v[2:3], s[20:21] op_sel_hi:[1,0]
	v_pk_fma_f32 v[44:45], v[44:45], s[16:17], v[196:197] op_sel_hi:[1,0,0] neg_lo:[1,0,0] neg_hi:[1,0,0]
	v_mfma_f32_16x16x32_bf16 v[22:25], v[94:97], v[50:53], v[22:25]
	v_mul_f32_e64 v50, v6, v2
	v_mul_f32_e64 v51, v7, v3
	s_nop 0
	v_pk_mul_f32 v[18:19], v[30:31], v[18:19]
	v_pk_mul_f32 v[20:21], v[32:33], v[20:21]
	v_pk_mul_f32 v[18:19], v[26:27], v[18:19]
	v_pk_mul_f32 v[20:21], v[28:29], v[20:21]
	s_nop 0
	v_pk_mul_f32 v[22:23], v[102:103], v[22:23]
	v_pk_mul_f32 v[24:25], v[106:107], v[24:25]
	v_pk_mul_f32 v[22:23], v[34:35], v[22:23]
	v_pk_mul_f32 v[24:25], v[36:37], v[24:25]
	v_cvt_pk_bf16_f32 v18, v18, v19
	v_cvt_pk_bf16_f32 v19, v20, v21
	v_cvt_pk_bf16_f32 v20, v22, v23
	v_pk_mul_f32 v[2:3], v[4:5], s[20:21] op_sel_hi:[1,0]
	v_cvt_pk_bf16_f32 v21, v24, v25
	global_store_dwordx4 v[38:39], v[18:21], off
	global_load_dword v18, v[200:201], off offset:192
	s_nop 0
	global_load_dwordx4 v[22:25], v[104:105], off
	global_load_dwordx4 v[26:29], v[104:105], off offset:64
	global_load_dwordx4 v[30:33], v[104:105], off offset:128
	global_load_dwordx4 v[34:37], v[104:105], off offset:192
	v_pk_mul_f32 v[20:21], v[12:13], v[12:13]
	v_pk_mul_f32 v[38:39], v[10:11], v[10:11]
	v_pk_mul_f32 v[52:53], v[8:9], v[4:5]
	v_pk_fma_f32 v[4:5], v[38:39], s[16:17], v[196:197] op_sel_hi:[1,0,0] neg_lo:[1,0,0] neg_hi:[1,0,0]
	v_pk_fma_f32 v[20:21], v[20:21], s[16:17], v[196:197] op_sel_hi:[1,0,0] neg_lo:[1,0,0] neg_hi:[1,0,0]
	v_exp_f32_e32 v38, v40
	v_exp_f32_e32 v39, v41
	v_exp_f32_e32 v40, v42
	v_exp_f32_e32 v41, v43
	v_pk_fma_f32 v[42:43], v[46:47], s[16:17], v[196:197] op_sel_hi:[1,0,0] neg_lo:[1,0,0] neg_hi:[1,0,0]
	v_exp_f32_e32 v46, v48
	v_exp_f32_e32 v47, v49
	v_exp_f32_e32 v48, v2
	v_exp_f32_e32 v49, v3
	v_pk_mul_f32 v[2:3], v[10:11], v[4:5]
	v_pk_mul_f32 v[4:5], v[12:13], v[20:21]
	v_pk_mul_f32 v[14:15], v[10:11], v[14:15]
	v_pk_mul_f32 v[16:17], v[12:13], v[16:17]
	v_pk_mul_f32 v[6:7], v[6:7], v[42:43]
	v_pk_mul_f32 v[8:9], v[8:9], v[44:45]
	v_exp_f32_e32 v10, v2
	v_exp_f32_e32 v11, v3
	v_exp_f32_e32 v12, v4
	v_exp_f32_e32 v13, v5
	v_exp_f32_e32 v42, v6
	v_exp_f32_e32 v43, v7
	v_exp_f32_e32 v44, v8
	v_exp_f32_e32 v45, v9
	v_pk_add_f32 v[38:39], v[38:39], 1.0 op_sel_hi:[1,0]
	v_pk_add_f32 v[40:41], v[40:41], 1.0 op_sel_hi:[1,0]
	v_pk_add_f32 v[46:47], v[46:47], 1.0 op_sel_hi:[1,0]
	v_pk_add_f32 v[48:49], v[48:49], 1.0 op_sel_hi:[1,0]
	v_pk_fma_f32 v[10:11], v[10:11], v[38:39], v[38:39]
	v_pk_fma_f32 v[12:13], v[12:13], v[40:41], v[40:41]
	v_rcp_f32_e32 v10, v10
	v_rcp_f32_e32 v11, v11
	v_rcp_f32_e32 v12, v12
	v_rcp_f32_e32 v13, v13
	s_waitcnt vmcnt(4)
	v_mov_b32_e32 v19, v18
	v_mov_b32_e32 v20, v18
	v_mov_b32_e32 v21, v18
	s_waitcnt vmcnt(3)
	s_nop 0
	v_mfma_f32_16x16x32_bf16 v[2:5], v[70:73], v[22:25], v[18:21]
	v_mfma_f32_16x16x32_bf16 v[6:9], v[66:69], v[22:25], v[18:21]
	v_add_u32_e32 v22, s23, v100
	v_mad_i64_i32 v[22:23], s[4:5], v22, s61, v[198:199]
	s_waitcnt vmcnt(2)
	v_mfma_f32_16x16x32_bf16 v[2:5], v[78:81], v[26:29], v[2:5]
	v_fma_f32 v18, v42, v46, v46
	v_fma_f32 v19, v43, v47, v47
	v_pk_fma_f32 v[20:21], v[44:45], v[48:49], v[48:49]
	v_rcp_f32_e32 v18, v18
	v_mfma_f32_16x16x32_bf16 v[6:9], v[74:77], v[26:29], v[6:9]
	v_rcp_f32_e32 v19, v19
	v_rcp_f32_e32 v20, v20
	v_rcp_f32_e32 v21, v21
	s_waitcnt vmcnt(1)
	v_mfma_f32_16x16x32_bf16 v[2:5], v[86:89], v[30:33], v[2:5]
	v_lshl_add_u64 v[22:23], v[22:23], 0, s[40:41]
	v_lshl_add_u64 v[22:23], v[22:23], 0, s[6:7]
	v_lshl_add_u64 v[22:23], v[22:23], 0, v[186:187]
	v_mfma_f32_16x16x32_bf16 v[6:9], v[82:85], v[30:33], v[6:9]
	s_mov_b64 s[4:5], -1
	s_waitcnt vmcnt(0)
	v_mfma_f32_16x16x32_bf16 v[2:5], v[90:93], v[34:37], v[2:5]
	v_mfma_f32_16x16x32_bf16 v[6:9], v[94:97], v[34:37], v[6:9]
	s_nop 6
	v_mul_f32_e64 v2, v14, v2
	v_mul_f32_e64 v3, v15, v3
	v_pk_mul_f32 v[4:5], v[16:17], v[4:5]
	v_pk_mul_f32 v[6:7], v[50:51], v[6:7]
	v_pk_mul_f32 v[8:9], v[52:53], v[8:9]
	v_pk_mul_f32 v[2:3], v[10:11], v[2:3]
	v_pk_mul_f32 v[4:5], v[12:13], v[4:5]
	v_pk_mul_f32 v[6:7], v[18:19], v[6:7]
	v_pk_mul_f32 v[8:9], v[20:21], v[8:9]
	v_cvt_pk_bf16_f32 v2, v2, v3
	v_cvt_pk_bf16_f32 v3, v4, v5
	v_cvt_pk_bf16_f32 v4, v6, v7
	s_nop 0
	v_cvt_pk_bf16_f32 v5, v8, v9
	global_store_dwordx4 v[22:23], v[2:5], off
	s_cbranch_vccnz .LBB0_1123
	s_andn2_b64 vcc, exec, s[10:11]
	s_cbranch_vccnz .LBB0_1122
	s_barrier
	s_branch .LBB0_1122
